# v81 + load-segment vmcnt and lgkmcnt waits merged into one s_waitcnt (one instruction less before each closing barrier), bursts at phase 4
# speedup vs baseline: 1.0009x; 1.0009x over previous
; #define PG8_STAGE(bufoff, gbase, voff) do { _Pragma("unroll") for (int _i = 0; _i < 2; ++_i) \
;         __builtin_amdgcn_global_load_lds((const unsigned*)((const char*)(gbase) + (voff)[_i]), (PG8_LAS unsigned*)(lds + (bufoff) + ldsw + _i * 8192), 16, 0, 0); } while (0)
; #define PG8_STAGE_NT(bufoff, gbase, voff) do { _Pragma("unroll") for (int _i = 0; _i < 2; ++_i) \
;         __builtin_amdgcn_global_load_lds((const unsigned*)((const char*)(gbase) + (voff)[_i]), (PG8_LAS unsigned*)(lds + (bufoff) + ldsw + _i * 8192), 16, 0, PG8_B_AUX); } while (0)
; #define PG8_LDA(dst, b, h) do { _Pragma("unroll") for (int m = 0; m < 4; ++m) _Pragma("unroll") for (int k = 0; k < 2; ++k) dst[m][k] = *(const PG8_LAS bf16x8*)(lds + PG8_SA(b, h) + aoff + m * 2048 + k * 1024); } while (0)
; #define PG8_LDB(dst, b, h) do { _Pragma("unroll") for (int n = 0; n < 2; ++n) _Pragma("unroll") for (int k = 0; k < 2; ++k) dst[n][k] = *(const PG8_LAS bf16x8*)(lds + PG8_SB(b, h) + boff + n * 2048 + k * 1024); } while (0)
; #define PG8_WAIT_V(n) asm volatile("s_waitcnt vmcnt(" #n ")" ::: "memory")
; #define PG8_WAIT_L(n) asm volatile("s_waitcnt lgkmcnt(" #n ")" ::: "memory")
; #define PG8_BAR __builtin_amdgcn_s_barrier()
; #define PG8_SCHED __builtin_amdgcn_sched_barrier(0)
; template <class Epi, class Sched, bool ALIGN_EPI = false, bool SP2 = false>
; __device__ __forceinline__ void gemm_phase(PG8_LAS unsigned char* lds, const Gemm g, const Sched& S, const Epi& E, int wid) {
;     ...
;             const bool last = (t == nt - 2);
;             const char* a1 = cA + (size_t)(t + 1) * kstep;
;             const char* a2 = last ? nA : cA + (size_t)(t + 2) * kstep; const char* b2 = last ? nB : cB + (size_t)(t + 2) * kstep;
;             const char* a3 = a2 + kstep; const char* b3 = b2 + kstep;
;             if (last && has_next) S.a_ready(nxt);
;             if constexpr (SP2) {
;             PG8_LDB(B0, 0, 0); PG8_LDB(B1, 0, 1); PG8_SCHED; PG8_LDA(At, 0, 0); PG8_STAGE(PG8_SA(1, 1), a1 + hstepA, voffA);
;             PG8_WAIT_V(8); PG8_WAIT_L(0); PG8_BAR; PG8_MMA(0, 0, At, B0); PG8_MMA(0, 1, At, B1); PG8_BAR; PG8_SCHED;
;             PG8_LDA(At, 0, 1); PG8_STAGE_NT(PG8_SB(0, 0), b2, voffB); PG8_STAGE_NT(PG8_SB(0, 1), b2 + hstepB, voffB); PG8_STAGE(PG8_SA(0, 0), a2, voffA);
;             PG8_WAIT_V(8); PG8_WAIT_L(0); PG8_BAR; PG8_MMA(1, 0, At, B0); PG8_MMA(1, 1, At, B1); PG8_BAR; PG8_SCHED;
.LBB0_233:
	ds_read_b128 v[144:147], v155
	ds_read_b128 v[148:151], v155 offset:1024
	ds_read_b128 v[160:163], v155 offset:2048
	ds_read_b128 v[164:167], v155 offset:3072
	ds_read_b128 v[168:171], v156
	ds_read_b128 v[172:175], v156 offset:1024
	ds_read_b128 v[176:179], v156 offset:2048
	ds_read_b128 v[180:183], v156 offset:3072
	s_add_u32 s4, s48, 0x100
	s_addc_u32 s5, s49, 0
	s_add_u32 s98, s48, 0x80
	s_addc_u32 s99, s49, 0
	s_add_u32 s100, s48, 0x104080
	s_addc_u32 s101, s49, 0
	s_cmp_eq_u32 s66, 60
	s_cselect_b32 s53, s45, s5
	s_cselect_b32 s52, s44, s4
	s_cselect_b32 s51, s47, s65
	s_cselect_b32 s50, s46, s64
	s_add_i32 m0, s23, 0xc000
	ds_read_b128 v[184:187], v157
	ds_read_b128 v[188:191], v157 offset:1024
	ds_read_b128 v[192:195], v157 offset:2048
	ds_read_b128 v[196:199], v157 offset:3072
	ds_read_b128 v[200:203], v157 offset:4096
	ds_read_b128 v[204:207], v157 offset:5120
	ds_read_b128 v[208:211], v157 offset:6144
	ds_read_b128 v[212:215], v157 offset:7168
	global_load_lds_dwordx4 v134, s[100:101]
	s_add_i32 m0, s23, 0xe000
	s_nop 0
	global_load_lds_dwordx4 v130, s[100:101]
	s_mov_b32 m0, s55
	s_nop 0
	global_load_lds_dwordx4 v134, s[98:99]
	s_mov_b32 m0, s56
	s_nop 0
	global_load_lds_dwordx4 v130, s[98:99]
	s_waitcnt vmcnt(8) lgkmcnt(0)
	s_barrier
	v_mfma_f32_16x16x32_bf16 v[112:115], v[144:147], v[184:187], v[112:115]
	v_mfma_f32_16x16x32_bf16 v[108:111], v[160:163], v[184:187], v[108:111]
	v_mfma_f32_16x16x32_bf16 v[104:107], v[144:147], v[192:195], v[104:107]
	v_mfma_f32_16x16x32_bf16 v[100:103], v[160:163], v[192:195], v[100:103]
	v_mfma_f32_16x16x32_bf16 v[92:95], v[144:147], v[200:203], v[92:95]
	v_mfma_f32_16x16x32_bf16 v[84:87], v[160:163], v[200:203], v[84:87]
	v_mfma_f32_16x16x32_bf16 v[76:79], v[144:147], v[208:211], v[76:79]
	v_mfma_f32_16x16x32_bf16 v[68:71], v[160:163], v[208:211], v[68:71]
	v_mfma_f32_16x16x32_bf16 v[112:115], v[148:151], v[188:191], v[112:115]
	v_mfma_f32_16x16x32_bf16 v[108:111], v[164:167], v[188:191], v[108:111]
	v_mfma_f32_16x16x32_bf16 v[104:107], v[148:151], v[196:199], v[104:107]
	v_mfma_f32_16x16x32_bf16 v[100:103], v[164:167], v[196:199], v[100:103]
	v_mfma_f32_16x16x32_bf16 v[92:95], v[148:151], v[204:207], v[92:95]
	v_mfma_f32_16x16x32_bf16 v[84:87], v[164:167], v[204:207], v[84:87]
	v_mfma_f32_16x16x32_bf16 v[76:79], v[148:151], v[212:215], v[76:79]
	v_mfma_f32_16x16x32_bf16 v[68:71], v[164:167], v[212:215], v[68:71]
	v_mfma_f32_16x16x32_bf16 v[124:127], v[168:171], v[184:187], v[124:127]
	v_mfma_f32_16x16x32_bf16 v[120:123], v[176:179], v[184:187], v[120:123]
	v_mfma_f32_16x16x32_bf16 v[116:119], v[168:171], v[192:195], v[116:119]
	v_mfma_f32_16x16x32_bf16 v[96:99], v[176:179], v[192:195], v[96:99]
	v_mfma_f32_16x16x32_bf16 v[88:91], v[168:171], v[200:203], v[88:91]
	v_mfma_f32_16x16x32_bf16 v[80:83], v[176:179], v[200:203], v[80:83]
	v_mfma_f32_16x16x32_bf16 v[72:75], v[168:171], v[208:211], v[72:75]
	v_mfma_f32_16x16x32_bf16 v[64:67], v[176:179], v[208:211], v[64:67]
	v_mfma_f32_16x16x32_bf16 v[124:127], v[172:175], v[188:191], v[124:127]
	v_mfma_f32_16x16x32_bf16 v[120:123], v[180:183], v[188:191], v[120:123]
	v_mfma_f32_16x16x32_bf16 v[116:119], v[172:175], v[196:199], v[116:119]
	v_mfma_f32_16x16x32_bf16 v[96:99], v[180:183], v[196:199], v[96:99]
	v_mfma_f32_16x16x32_bf16 v[88:91], v[172:175], v[204:207], v[88:91]
	v_mfma_f32_16x16x32_bf16 v[80:83], v[180:183], v[204:207], v[80:83]
	v_mfma_f32_16x16x32_bf16 v[72:75], v[172:175], v[212:215], v[72:75]
	v_mfma_f32_16x16x32_bf16 v[64:67], v[180:183], v[212:215], v[64:67]
	s_barrier
	s_add_i32 s48, s58, s17
	s_mov_b32 m0, s48
	ds_read_b128 v[184:187], v157 offset:16384
	ds_read_b128 v[188:191], v157 offset:17408
	ds_read_b128 v[192:195], v157 offset:18432
	ds_read_b128 v[196:199], v157 offset:19456
	ds_read_b128 v[200:203], v157 offset:20480
	ds_read_b128 v[204:207], v157 offset:21504
	ds_read_b128 v[208:211], v157 offset:22528
	ds_read_b128 v[212:215], v157 offset:23552
	global_load_lds_dwordx4 v132, s[50:51]
	s_add_i32 m0, s48, 0x2000
	s_add_u32 s48, s50, 0x104000
	s_addc_u32 s49, s51, 0
	s_add_i32 s67, s59, s17
	global_load_lds_dwordx4 v128, s[50:51]
	s_mov_b32 m0, s67
	s_nop 0
	global_load_lds_dwordx4 v132, s[48:49]
	s_add_i32 m0, s67, 0x2000
	s_nop 0
	global_load_lds_dwordx4 v128, s[48:49]
	s_waitcnt vmcnt(4) lgkmcnt(0)
	s_barrier
	v_mfma_f32_16x16x32_bf16 v[60:63], v[144:147], v[184:187], v[60:63]
	v_mfma_f32_16x16x32_bf16 v[52:55], v[160:163], v[184:187], v[52:55]
	v_mfma_f32_16x16x32_bf16 v[44:47], v[144:147], v[192:195], v[44:47]
	v_mfma_f32_16x16x32_bf16 v[36:39], v[160:163], v[192:195], v[36:39]
	v_mfma_f32_16x16x32_bf16 v[28:31], v[144:147], v[200:203], v[28:31]
	v_mfma_f32_16x16x32_bf16 v[20:23], v[160:163], v[200:203], v[20:23]
	v_mfma_f32_16x16x32_bf16 v[12:15], v[144:147], v[208:211], v[12:15]
	v_mfma_f32_16x16x32_bf16 v[4:7], v[160:163], v[208:211], v[4:7]
	v_mfma_f32_16x16x32_bf16 v[60:63], v[148:151], v[188:191], v[60:63]
	v_mfma_f32_16x16x32_bf16 v[52:55], v[164:167], v[188:191], v[52:55]
	v_mfma_f32_16x16x32_bf16 v[44:47], v[148:151], v[196:199], v[44:47]
	v_mfma_f32_16x16x32_bf16 v[36:39], v[164:167], v[196:199], v[36:39]
	v_mfma_f32_16x16x32_bf16 v[28:31], v[148:151], v[204:207], v[28:31]
	v_mfma_f32_16x16x32_bf16 v[20:23], v[164:167], v[204:207], v[20:23]
	v_mfma_f32_16x16x32_bf16 v[12:15], v[148:151], v[212:215], v[12:15]
	v_mfma_f32_16x16x32_bf16 v[4:7], v[164:167], v[212:215], v[4:7]
	v_mfma_f32_16x16x32_bf16 v[56:59], v[168:171], v[184:187], v[56:59]
	v_mfma_f32_16x16x32_bf16 v[48:51], v[176:179], v[184:187], v[48:51]
	v_mfma_f32_16x16x32_bf16 v[40:43], v[168:171], v[192:195], v[40:43]
	v_mfma_f32_16x16x32_bf16 v[32:35], v[176:179], v[192:195], v[32:35]
	v_mfma_f32_16x16x32_bf16 v[24:27], v[168:171], v[200:203], v[24:27]
	v_mfma_f32_16x16x32_bf16 v[16:19], v[176:179], v[200:203], v[16:19]
	v_mfma_f32_16x16x32_bf16 v[8:11], v[168:171], v[208:211], v[8:11]
	v_mfma_f32_16x16x32_bf16 v[0:3], v[176:179], v[208:211], v[0:3]
	v_mfma_f32_16x16x32_bf16 v[56:59], v[172:175], v[188:191], v[56:59]
	v_mfma_f32_16x16x32_bf16 v[48:51], v[180:183], v[188:191], v[48:51]
	v_mfma_f32_16x16x32_bf16 v[40:43], v[172:175], v[196:199], v[40:43]
	v_mfma_f32_16x16x32_bf16 v[32:35], v[180:183], v[196:199], v[32:35]
	v_mfma_f32_16x16x32_bf16 v[24:27], v[172:175], v[204:207], v[24:27]
	v_mfma_f32_16x16x32_bf16 v[16:19], v[180:183], v[204:207], v[16:19]
	v_mfma_f32_16x16x32_bf16 v[8:11], v[172:175], v[212:215], v[8:11]
	v_mfma_f32_16x16x32_bf16 v[0:3], v[180:183], v[212:215], v[0:3]
	s_barrier
; #define PG8_STAGE(bufoff, gbase, voff) do { _Pragma("unroll") for (int _i = 0; _i < 2; ++_i) \
;         __builtin_amdgcn_global_load_lds((const unsigned*)((const char*)(gbase) + (voff)[_i]), (PG8_LAS unsigned*)(lds + (bufoff) + ldsw + _i * 8192), 16, 0, 0); } while (0)
; #define PG8_STAGE_NT(bufoff, gbase, voff) do { _Pragma("unroll") for (int _i = 0; _i < 2; ++_i) \
;         __builtin_amdgcn_global_load_lds((const unsigned*)((const char*)(gbase) + (voff)[_i]), (PG8_LAS unsigned*)(lds + (bufoff) + ldsw + _i * 8192), 16, 0, PG8_B_AUX); } while (0)
; #define PG8_LDA(dst, b, h) do { _Pragma("unroll") for (int m = 0; m < 4; ++m) _Pragma("unroll") for (int k = 0; k < 2; ++k) dst[m][k] = *(const PG8_LAS bf16x8*)(lds + PG8_SA(b, h) + aoff + m * 2048 + k * 1024); } while (0)
; #define PG8_LDB(dst, b, h) do { _Pragma("unroll") for (int n = 0; n < 2; ++n) _Pragma("unroll") for (int k = 0; k < 2; ++k) dst[n][k] = *(const PG8_LAS bf16x8*)(lds + PG8_SB(b, h) + boff + n * 2048 + k * 1024); } while (0)
; #define PG8_MMA(ai, bj, At, Bt) do { __builtin_amdgcn_s_setprio(1); _Pragma("unroll") for (int m = 0; m < 4; ++m) _Pragma("unroll") for (int n = 0; n < 2; ++n) _Pragma("unroll") for (int k = 0; k < 2; ++k) \
;         acc[ai][bj][m][n] = __builtin_amdgcn_mfma_f32_16x16x32_bf16(Bt[n][k], At[m][k], acc[ai][bj][m][n], 0, 0, 0); __builtin_amdgcn_s_setprio(0); } while (0)
; #define PG8_WAIT_V(n) asm volatile("s_waitcnt vmcnt(" #n ")" ::: "memory")
; #define PG8_WAIT_L(n) asm volatile("s_waitcnt lgkmcnt(" #n ")" ::: "memory")
; #define PG8_BAR __builtin_amdgcn_s_barrier()
; #define PG8_SCHED __builtin_amdgcn_sched_barrier(0)
; template <class Epi, class Sched, bool ALIGN_EPI = false, bool SP2 = false>
; __device__ __forceinline__ void gemm_phase(PG8_LAS unsigned char* lds, const Gemm g, const Sched& S, const Epi& E, int wid) {
;     ...
;             PG8_LDB(B0, 1, 0); PG8_LDB(B1, 1, 1); PG8_SCHED; PG8_LDA(At, 1, 0); PG8_STAGE(PG8_SA(0, 1), a2 + hstepA, voffA);
;             PG8_WAIT_V(8); PG8_WAIT_L(0); PG8_BAR; PG8_MMA(0, 0, At, B0); PG8_MMA(0, 1, At, B1); PG8_BAR; PG8_SCHED;
;             PG8_LDA(At, 1, 1); PG8_STAGE_NT(PG8_SB(1, 0), b3, voffB); PG8_STAGE_NT(PG8_SB(1, 1), b3 + hstepB, voffB); PG8_STAGE(PG8_SA(1, 0), a3, voffA);
;             PG8_WAIT_V(8); PG8_WAIT_L(0); PG8_BAR; PG8_MMA(1, 0, At, B0); PG8_MMA(1, 1, At, B1); PG8_BAR; PG8_SCHED;
	s_add_i32 s67, 0, 0x18000
	v_add_u32_e32 v159, s67, v153
	s_add_i32 s68, 0, 0x1c000
	ds_read_b128 v[144:147], v159
	ds_read_b128 v[148:151], v159 offset:1024
	ds_read_b128 v[160:163], v159 offset:2048
	ds_read_b128 v[164:167], v159 offset:3072
	v_add_u32_e32 v159, s68, v153
	ds_read_b128 v[168:171], v159
	ds_read_b128 v[172:175], v159 offset:1024
	ds_read_b128 v[176:179], v159 offset:2048
	ds_read_b128 v[180:183], v159 offset:3072
	s_add_u32 s48, s52, 0x104000
	s_addc_u32 s49, s53, 0
	s_mov_b32 m0, s25
	ds_read_b128 v[184:187], v157 offset:32768
	ds_read_b128 v[188:191], v157 offset:33792
	ds_read_b128 v[192:195], v157 offset:34816
	ds_read_b128 v[196:199], v157 offset:35840
	ds_read_b128 v[200:203], v157 offset:36864
	ds_read_b128 v[204:207], v157 offset:37888
	ds_read_b128 v[208:211], v157 offset:38912
	ds_read_b128 v[212:215], v157 offset:39936
	global_load_lds_dwordx4 v134, s[48:49]
	s_mov_b32 m0, s29
	s_nop 0
	global_load_lds_dwordx4 v130, s[48:49]
	s_mov_b32 m0, s23
	s_nop 0
	global_load_lds_dwordx4 v134, s[52:53]
	s_mov_b32 m0, s24
	s_nop 0
	global_load_lds_dwordx4 v130, s[52:53]
	s_nop 0
	s_waitcnt vmcnt(8) lgkmcnt(0)
	s_barrier
	v_mfma_f32_16x16x32_bf16 v[112:115], v[144:147], v[184:187], v[112:115]
	v_mfma_f32_16x16x32_bf16 v[108:111], v[160:163], v[184:187], v[108:111]
	v_mfma_f32_16x16x32_bf16 v[104:107], v[144:147], v[192:195], v[104:107]
	v_mfma_f32_16x16x32_bf16 v[100:103], v[160:163], v[192:195], v[100:103]
	v_mfma_f32_16x16x32_bf16 v[92:95], v[144:147], v[200:203], v[92:95]
	v_mfma_f32_16x16x32_bf16 v[84:87], v[160:163], v[200:203], v[84:87]
	v_mfma_f32_16x16x32_bf16 v[76:79], v[144:147], v[208:211], v[76:79]
	v_mfma_f32_16x16x32_bf16 v[68:71], v[160:163], v[208:211], v[68:71]
	v_mfma_f32_16x16x32_bf16 v[112:115], v[148:151], v[188:191], v[112:115]
	v_mfma_f32_16x16x32_bf16 v[108:111], v[164:167], v[188:191], v[108:111]
	v_mfma_f32_16x16x32_bf16 v[104:107], v[148:151], v[196:199], v[104:107]
	v_mfma_f32_16x16x32_bf16 v[100:103], v[164:167], v[196:199], v[100:103]
	v_mfma_f32_16x16x32_bf16 v[92:95], v[148:151], v[204:207], v[92:95]
	v_mfma_f32_16x16x32_bf16 v[84:87], v[164:167], v[204:207], v[84:87]
	v_mfma_f32_16x16x32_bf16 v[76:79], v[148:151], v[212:215], v[76:79]
	v_mfma_f32_16x16x32_bf16 v[68:71], v[164:167], v[212:215], v[68:71]
	v_mfma_f32_16x16x32_bf16 v[124:127], v[168:171], v[184:187], v[124:127]
	v_mfma_f32_16x16x32_bf16 v[120:123], v[176:179], v[184:187], v[120:123]
	v_mfma_f32_16x16x32_bf16 v[116:119], v[168:171], v[192:195], v[116:119]
	v_mfma_f32_16x16x32_bf16 v[96:99], v[176:179], v[192:195], v[96:99]
	v_mfma_f32_16x16x32_bf16 v[88:91], v[168:171], v[200:203], v[88:91]
	v_mfma_f32_16x16x32_bf16 v[80:83], v[176:179], v[200:203], v[80:83]
	v_mfma_f32_16x16x32_bf16 v[72:75], v[168:171], v[208:211], v[72:75]
	v_mfma_f32_16x16x32_bf16 v[64:67], v[176:179], v[208:211], v[64:67]
	v_mfma_f32_16x16x32_bf16 v[124:127], v[172:175], v[188:191], v[124:127]
	v_mfma_f32_16x16x32_bf16 v[120:123], v[180:183], v[188:191], v[120:123]
	v_mfma_f32_16x16x32_bf16 v[116:119], v[172:175], v[196:199], v[116:119]
	v_mfma_f32_16x16x32_bf16 v[96:99], v[180:183], v[196:199], v[96:99]
	v_mfma_f32_16x16x32_bf16 v[88:91], v[172:175], v[204:207], v[88:91]
	v_mfma_f32_16x16x32_bf16 v[80:83], v[180:183], v[204:207], v[80:83]
	v_mfma_f32_16x16x32_bf16 v[72:75], v[172:175], v[212:215], v[72:75]
	v_mfma_f32_16x16x32_bf16 v[64:67], v[180:183], v[212:215], v[64:67]
	s_barrier
	s_add_i32 s48, s67, s17
	s_mov_b32 m0, s48
	s_add_u32 s98, s50, 0x80
	s_addc_u32 s99, s51, 0
	ds_read_b128 v[184:187], v157 offset:49152
	ds_read_b128 v[188:191], v157 offset:50176
	ds_read_b128 v[192:195], v157 offset:51200
	ds_read_b128 v[196:199], v157 offset:52224
	ds_read_b128 v[200:203], v157 offset:53248
	ds_read_b128 v[204:207], v157 offset:54272
	ds_read_b128 v[208:211], v157 offset:55296
	ds_read_b128 v[212:215], v157 offset:56320
	global_load_lds_dwordx4 v132, s[98:99]
	s_add_i32 m0, s48, 0x2000
	s_add_u32 s48, s50, 0x104080
	s_addc_u32 s49, s51, 0
	s_add_i32 s50, s68, s17
	global_load_lds_dwordx4 v128, s[98:99]
	s_mov_b32 m0, s50
	s_nop 0
	global_load_lds_dwordx4 v132, s[48:49]
	s_add_i32 m0, s50, 0x2000
	s_nop 0
	global_load_lds_dwordx4 v128, s[48:49]
	s_nop 0
	s_waitcnt vmcnt(4) lgkmcnt(0)
	s_barrier
	v_mfma_f32_16x16x32_bf16 v[60:63], v[144:147], v[184:187], v[60:63]
	v_mfma_f32_16x16x32_bf16 v[52:55], v[160:163], v[184:187], v[52:55]
	v_mfma_f32_16x16x32_bf16 v[44:47], v[144:147], v[192:195], v[44:47]
	v_mfma_f32_16x16x32_bf16 v[36:39], v[160:163], v[192:195], v[36:39]
	v_mfma_f32_16x16x32_bf16 v[28:31], v[144:147], v[200:203], v[28:31]
	v_mfma_f32_16x16x32_bf16 v[20:23], v[160:163], v[200:203], v[20:23]
	v_mfma_f32_16x16x32_bf16 v[12:15], v[144:147], v[208:211], v[12:15]
	v_mfma_f32_16x16x32_bf16 v[4:7], v[160:163], v[208:211], v[4:7]
	v_mfma_f32_16x16x32_bf16 v[60:63], v[148:151], v[188:191], v[60:63]
	v_mfma_f32_16x16x32_bf16 v[52:55], v[164:167], v[188:191], v[52:55]
	v_mfma_f32_16x16x32_bf16 v[44:47], v[148:151], v[196:199], v[44:47]
	v_mfma_f32_16x16x32_bf16 v[36:39], v[164:167], v[196:199], v[36:39]
	v_mfma_f32_16x16x32_bf16 v[28:31], v[148:151], v[204:207], v[28:31]
	v_mfma_f32_16x16x32_bf16 v[20:23], v[164:167], v[204:207], v[20:23]
	v_mfma_f32_16x16x32_bf16 v[12:15], v[148:151], v[212:215], v[12:15]
	v_mfma_f32_16x16x32_bf16 v[4:7], v[164:167], v[212:215], v[4:7]
	v_mfma_f32_16x16x32_bf16 v[56:59], v[168:171], v[184:187], v[56:59]
	v_mfma_f32_16x16x32_bf16 v[48:51], v[176:179], v[184:187], v[48:51]
	v_mfma_f32_16x16x32_bf16 v[40:43], v[168:171], v[192:195], v[40:43]
	v_mfma_f32_16x16x32_bf16 v[32:35], v[176:179], v[192:195], v[32:35]
	v_mfma_f32_16x16x32_bf16 v[24:27], v[168:171], v[200:203], v[24:27]
	v_mfma_f32_16x16x32_bf16 v[16:19], v[176:179], v[200:203], v[16:19]
	v_mfma_f32_16x16x32_bf16 v[8:11], v[168:171], v[208:211], v[8:11]
	v_mfma_f32_16x16x32_bf16 v[0:3], v[176:179], v[208:211], v[0:3]
	v_mfma_f32_16x16x32_bf16 v[56:59], v[172:175], v[188:191], v[56:59]
	v_mfma_f32_16x16x32_bf16 v[48:51], v[180:183], v[188:191], v[48:51]
	v_mfma_f32_16x16x32_bf16 v[40:43], v[172:175], v[196:199], v[40:43]
	v_mfma_f32_16x16x32_bf16 v[32:35], v[180:183], v[196:199], v[32:35]
	v_mfma_f32_16x16x32_bf16 v[24:27], v[172:175], v[204:207], v[24:27]
	v_mfma_f32_16x16x32_bf16 v[16:19], v[180:183], v[204:207], v[16:19]
	v_mfma_f32_16x16x32_bf16 v[8:11], v[172:175], v[212:215], v[8:11]
	v_mfma_f32_16x16x32_bf16 v[0:3], v[180:183], v[212:215], v[0:3]
	s_barrier
	s_add_i32 s66, s66, 2
	s_add_u32 s64, s64, 0x100
	s_addc_u32 s65, s65, 0
	s_cmp_gt_u32 s66, 61
	s_mov_b64 s[48:49], s[4:5]
	s_cbranch_scc0 .LBB0_233
	s_and_b64 vcc, exec, s[42:43]
	s_cbranch_vccz .LBB0_236
	s_barrier

; #define PG8_STAGE(bufoff, gbase, voff) do { _Pragma("unroll") for (int _i = 0; _i < 2; ++_i) \
;         __builtin_amdgcn_global_load_lds((const unsigned*)((const char*)(gbase) + (voff)[_i]), (PG8_LAS unsigned*)(lds + (bufoff) + ldsw + _i * 8192), 16, 0, 0); } while (0)
; #define PG8_STAGE_NT(bufoff, gbase, voff) do { _Pragma("unroll") for (int _i = 0; _i < 2; ++_i) \
;         __builtin_amdgcn_global_load_lds((const unsigned*)((const char*)(gbase) + (voff)[_i]), (PG8_LAS unsigned*)(lds + (bufoff) + ldsw + _i * 8192), 16, 0, PG8_B_AUX); } while (0)
; #define PG8_LDA(dst, b, h) do { _Pragma("unroll") for (int m = 0; m < 4; ++m) _Pragma("unroll") for (int k = 0; k < 2; ++k) dst[m][k] = *(const PG8_LAS bf16x8*)(lds + PG8_SA(b, h) + aoff + m * 2048 + k * 1024); } while (0)
; #define PG8_LDB(dst, b, h) do { _Pragma("unroll") for (int n = 0; n < 2; ++n) _Pragma("unroll") for (int k = 0; k < 2; ++k) dst[n][k] = *(const PG8_LAS bf16x8*)(lds + PG8_SB(b, h) + boff + n * 2048 + k * 1024); } while (0)
; #define PG8_WAIT_V(n) asm volatile("s_waitcnt vmcnt(" #n ")" ::: "memory")
; #define PG8_WAIT_L(n) asm volatile("s_waitcnt lgkmcnt(" #n ")" ::: "memory")
; #define PG8_BAR __builtin_amdgcn_s_barrier()
; #define PG8_SCHED __builtin_amdgcn_sched_barrier(0)
; template <class Epi, class Sched, bool ALIGN_EPI = false, bool SP2 = false>
; __device__ __forceinline__ void gemm_phase(PG8_LAS unsigned char* lds, const Gemm g, const Sched& S, const Epi& E, int wid) {
;     ...
;             const bool last = (t == nt - 2);
;             const char* a1 = cA + (size_t)(t + 1) * kstep;
;             const char* a2 = last ? nA : cA + (size_t)(t + 2) * kstep; const char* b2 = last ? nB : cB + (size_t)(t + 2) * kstep;
;             const char* a3 = a2 + kstep; const char* b3 = b2 + kstep;
;             if (last && has_next) S.a_ready(nxt);
;             if constexpr (SP2) {
;             PG8_LDB(B0, 0, 0); PG8_LDB(B1, 0, 1); PG8_SCHED; PG8_LDA(At, 0, 0); PG8_STAGE(PG8_SA(1, 1), a1 + hstepA, voffA);
;             PG8_WAIT_V(8); PG8_WAIT_L(0); PG8_BAR; PG8_MMA(0, 0, At, B0); PG8_MMA(0, 1, At, B1); PG8_BAR; PG8_SCHED;
;             PG8_LDA(At, 0, 1); PG8_STAGE_NT(PG8_SB(0, 0), b2, voffB); PG8_STAGE_NT(PG8_SB(0, 1), b2 + hstepB, voffB); PG8_STAGE(PG8_SA(0, 0), a2, voffA);
;             PG8_WAIT_V(8); PG8_WAIT_L(0); PG8_BAR; PG8_MMA(1, 0, At, B0); PG8_MMA(1, 1, At, B1); PG8_BAR; PG8_SCHED;
.LBB0_317:
	ds_read_b128 v[128:131], v205
	ds_read_b128 v[132:135], v205 offset:1024
	ds_read_b128 v[136:139], v205 offset:2048
	ds_read_b128 v[140:143], v205 offset:3072
	ds_read_b128 v[144:147], v206
	ds_read_b128 v[148:151], v206 offset:1024
	ds_read_b128 v[152:155], v206 offset:2048
	ds_read_b128 v[156:159], v206 offset:3072
	s_add_u32 s48, s46, 0x100
	s_addc_u32 s49, s47, 0
	s_add_u32 s98, s46, 0x80
	s_addc_u32 s99, s47, 0
	s_add_u32 s100, s46, 0x2b4080
	s_addc_u32 s101, s47, 0
	s_cmpk_eq_i32 s64, 0xa8
	s_cselect_b32 s53, s7, s49
	s_cselect_b32 s52, s6, s48
	s_cselect_b32 s51, s45, s63
	s_cselect_b32 s50, s44, s62
	s_add_i32 m0, s19, 0xc000
	ds_read_b128 v[160:163], v207
	ds_read_b128 v[164:167], v207 offset:1024
	ds_read_b128 v[184:187], v207 offset:2048
	ds_read_b128 v[188:191], v207 offset:3072
	ds_read_b128 v[192:195], v207 offset:4096
	ds_read_b128 v[196:199], v207 offset:5120
	ds_read_b128 v[210:213], v207 offset:6144
	ds_read_b128 v[214:217], v207 offset:7168
	global_load_lds_dwordx4 v168, s[100:101]
	s_add_i32 m0, s19, 0xe000
	s_nop 0
	global_load_lds_dwordx4 v172, s[100:101]
	s_mov_b32 m0, s29
	s_nop 0
	global_load_lds_dwordx4 v168, s[98:99]
	s_mov_b32 m0, s54
	s_nop 0
	global_load_lds_dwordx4 v172, s[98:99]
	s_waitcnt vmcnt(8) lgkmcnt(0)
	s_barrier
	v_mfma_f32_16x16x32_bf16 v[124:127], v[128:131], v[160:163], v[124:127]
	v_mfma_f32_16x16x32_bf16 v[120:123], v[136:139], v[160:163], v[120:123]
	v_mfma_f32_16x16x32_bf16 v[116:119], v[128:131], v[184:187], v[116:119]
	v_mfma_f32_16x16x32_bf16 v[112:115], v[136:139], v[184:187], v[112:115]
	v_mfma_f32_16x16x32_bf16 v[92:95], v[128:131], v[192:195], v[92:95]
	v_mfma_f32_16x16x32_bf16 v[88:91], v[136:139], v[192:195], v[88:91]
	v_mfma_f32_16x16x32_bf16 v[76:79], v[128:131], v[210:213], v[76:79]
	v_mfma_f32_16x16x32_bf16 v[72:75], v[136:139], v[210:213], v[72:75]
	v_mfma_f32_16x16x32_bf16 v[124:127], v[132:135], v[164:167], v[124:127]
	v_mfma_f32_16x16x32_bf16 v[120:123], v[140:143], v[164:167], v[120:123]
	v_mfma_f32_16x16x32_bf16 v[116:119], v[132:135], v[188:191], v[116:119]
	v_mfma_f32_16x16x32_bf16 v[112:115], v[140:143], v[188:191], v[112:115]
	v_mfma_f32_16x16x32_bf16 v[92:95], v[132:135], v[196:199], v[92:95]
	v_mfma_f32_16x16x32_bf16 v[88:91], v[140:143], v[196:199], v[88:91]
	v_mfma_f32_16x16x32_bf16 v[76:79], v[132:135], v[214:217], v[76:79]
	v_mfma_f32_16x16x32_bf16 v[72:75], v[140:143], v[214:217], v[72:75]
	v_mfma_f32_16x16x32_bf16 v[108:111], v[144:147], v[160:163], v[108:111]
	v_mfma_f32_16x16x32_bf16 v[104:107], v[152:155], v[160:163], v[104:107]
	v_mfma_f32_16x16x32_bf16 v[100:103], v[144:147], v[184:187], v[100:103]
	v_mfma_f32_16x16x32_bf16 v[96:99], v[152:155], v[184:187], v[96:99]
	v_mfma_f32_16x16x32_bf16 v[84:87], v[144:147], v[192:195], v[84:87]
	v_mfma_f32_16x16x32_bf16 v[80:83], v[152:155], v[192:195], v[80:83]
	v_mfma_f32_16x16x32_bf16 v[68:71], v[144:147], v[210:213], v[68:71]
	v_mfma_f32_16x16x32_bf16 v[64:67], v[152:155], v[210:213], v[64:67]
	v_mfma_f32_16x16x32_bf16 v[108:111], v[148:151], v[164:167], v[108:111]
	v_mfma_f32_16x16x32_bf16 v[104:107], v[156:159], v[164:167], v[104:107]
	v_mfma_f32_16x16x32_bf16 v[100:103], v[148:151], v[188:191], v[100:103]
	v_mfma_f32_16x16x32_bf16 v[96:99], v[156:159], v[188:191], v[96:99]
	v_mfma_f32_16x16x32_bf16 v[84:87], v[148:151], v[196:199], v[84:87]
	v_mfma_f32_16x16x32_bf16 v[80:83], v[156:159], v[196:199], v[80:83]
	v_mfma_f32_16x16x32_bf16 v[68:71], v[148:151], v[214:217], v[68:71]
	v_mfma_f32_16x16x32_bf16 v[64:67], v[156:159], v[214:217], v[64:67]
	s_barrier
	s_add_i32 s46, s57, s17
	s_mov_b32 m0, s46
	ds_read_b128 v[160:163], v207 offset:16384
	ds_read_b128 v[164:167], v207 offset:17408
	ds_read_b128 v[184:187], v207 offset:18432
	ds_read_b128 v[188:191], v207 offset:19456
	ds_read_b128 v[192:195], v207 offset:20480
	ds_read_b128 v[196:199], v207 offset:21504
	ds_read_b128 v[210:213], v207 offset:22528
	ds_read_b128 v[214:217], v207 offset:23552
	global_load_lds_dwordx4 v170, s[50:51]
	s_add_i32 m0, s46, 0x2000
	s_add_u32 s46, s50, 0x2b4000
	s_addc_u32 s47, s51, 0
	s_add_i32 s65, s58, s17
	global_load_lds_dwordx4 v174, s[50:51]
	s_mov_b32 m0, s65
	s_nop 0
	global_load_lds_dwordx4 v170, s[46:47]
	s_add_i32 m0, s65, 0x2000
	s_nop 0
	global_load_lds_dwordx4 v174, s[46:47]
	s_waitcnt vmcnt(4) lgkmcnt(0)
	s_barrier
	v_mfma_f32_16x16x32_bf16 v[60:63], v[128:131], v[160:163], v[60:63]
	v_mfma_f32_16x16x32_bf16 v[56:59], v[136:139], v[160:163], v[56:59]
	v_mfma_f32_16x16x32_bf16 v[44:47], v[128:131], v[184:187], v[44:47]
	v_mfma_f32_16x16x32_bf16 v[40:43], v[136:139], v[184:187], v[40:43]
	v_mfma_f32_16x16x32_bf16 v[28:31], v[128:131], v[192:195], v[28:31]
	v_mfma_f32_16x16x32_bf16 v[24:27], v[136:139], v[192:195], v[24:27]
	v_mfma_f32_16x16x32_bf16 v[12:15], v[128:131], v[210:213], v[12:15]
	v_mfma_f32_16x16x32_bf16 v[8:11], v[136:139], v[210:213], v[8:11]
	v_mfma_f32_16x16x32_bf16 v[60:63], v[132:135], v[164:167], v[60:63]
	v_mfma_f32_16x16x32_bf16 v[56:59], v[140:143], v[164:167], v[56:59]
	v_mfma_f32_16x16x32_bf16 v[44:47], v[132:135], v[188:191], v[44:47]
	v_mfma_f32_16x16x32_bf16 v[40:43], v[140:143], v[188:191], v[40:43]
	v_mfma_f32_16x16x32_bf16 v[28:31], v[132:135], v[196:199], v[28:31]
	v_mfma_f32_16x16x32_bf16 v[24:27], v[140:143], v[196:199], v[24:27]
	v_mfma_f32_16x16x32_bf16 v[12:15], v[132:135], v[214:217], v[12:15]
	v_mfma_f32_16x16x32_bf16 v[8:11], v[140:143], v[214:217], v[8:11]
	v_mfma_f32_16x16x32_bf16 v[52:55], v[144:147], v[160:163], v[52:55]
	v_mfma_f32_16x16x32_bf16 v[48:51], v[152:155], v[160:163], v[48:51]
	v_mfma_f32_16x16x32_bf16 v[36:39], v[144:147], v[184:187], v[36:39]
	v_mfma_f32_16x16x32_bf16 v[32:35], v[152:155], v[184:187], v[32:35]
	v_mfma_f32_16x16x32_bf16 v[20:23], v[144:147], v[192:195], v[20:23]
	v_mfma_f32_16x16x32_bf16 v[16:19], v[152:155], v[192:195], v[16:19]
	v_mfma_f32_16x16x32_bf16 v[4:7], v[144:147], v[210:213], v[4:7]
	v_mfma_f32_16x16x32_bf16 v[0:3], v[152:155], v[210:213], v[0:3]
	v_mfma_f32_16x16x32_bf16 v[52:55], v[148:151], v[164:167], v[52:55]
	v_mfma_f32_16x16x32_bf16 v[48:51], v[156:159], v[164:167], v[48:51]
	v_mfma_f32_16x16x32_bf16 v[36:39], v[148:151], v[188:191], v[36:39]
	v_mfma_f32_16x16x32_bf16 v[32:35], v[156:159], v[188:191], v[32:35]
	v_mfma_f32_16x16x32_bf16 v[20:23], v[148:151], v[196:199], v[20:23]
	v_mfma_f32_16x16x32_bf16 v[16:19], v[156:159], v[196:199], v[16:19]
	v_mfma_f32_16x16x32_bf16 v[4:7], v[148:151], v[214:217], v[4:7]
	v_mfma_f32_16x16x32_bf16 v[0:3], v[156:159], v[214:217], v[0:3]
	s_barrier
; #define PG8_STAGE(bufoff, gbase, voff) do { _Pragma("unroll") for (int _i = 0; _i < 2; ++_i) \
;         __builtin_amdgcn_global_load_lds((const unsigned*)((const char*)(gbase) + (voff)[_i]), (PG8_LAS unsigned*)(lds + (bufoff) + ldsw + _i * 8192), 16, 0, 0); } while (0)
; #define PG8_STAGE_NT(bufoff, gbase, voff) do { _Pragma("unroll") for (int _i = 0; _i < 2; ++_i) \
;         __builtin_amdgcn_global_load_lds((const unsigned*)((const char*)(gbase) + (voff)[_i]), (PG8_LAS unsigned*)(lds + (bufoff) + ldsw + _i * 8192), 16, 0, PG8_B_AUX); } while (0)
; #define PG8_LDA(dst, b, h) do { _Pragma("unroll") for (int m = 0; m < 4; ++m) _Pragma("unroll") for (int k = 0; k < 2; ++k) dst[m][k] = *(const PG8_LAS bf16x8*)(lds + PG8_SA(b, h) + aoff + m * 2048 + k * 1024); } while (0)
; #define PG8_LDB(dst, b, h) do { _Pragma("unroll") for (int n = 0; n < 2; ++n) _Pragma("unroll") for (int k = 0; k < 2; ++k) dst[n][k] = *(const PG8_LAS bf16x8*)(lds + PG8_SB(b, h) + boff + n * 2048 + k * 1024); } while (0)
; #define PG8_MMA(ai, bj, At, Bt) do { __builtin_amdgcn_s_setprio(1); _Pragma("unroll") for (int m = 0; m < 4; ++m) _Pragma("unroll") for (int n = 0; n < 2; ++n) _Pragma("unroll") for (int k = 0; k < 2; ++k) \
;         acc[ai][bj][m][n] = __builtin_amdgcn_mfma_f32_16x16x32_bf16(Bt[n][k], At[m][k], acc[ai][bj][m][n], 0, 0, 0); __builtin_amdgcn_s_setprio(0); } while (0)
; #define PG8_WAIT_V(n) asm volatile("s_waitcnt vmcnt(" #n ")" ::: "memory")
; #define PG8_WAIT_L(n) asm volatile("s_waitcnt lgkmcnt(" #n ")" ::: "memory")
; #define PG8_BAR __builtin_amdgcn_s_barrier()
; #define PG8_SCHED __builtin_amdgcn_sched_barrier(0)
; template <class Epi, class Sched, bool ALIGN_EPI = false, bool SP2 = false>
; __device__ __forceinline__ void gemm_phase(PG8_LAS unsigned char* lds, const Gemm g, const Sched& S, const Epi& E, int wid) {
;     ...
;             PG8_LDB(B0, 1, 0); PG8_LDB(B1, 1, 1); PG8_SCHED; PG8_LDA(At, 1, 0); PG8_STAGE(PG8_SA(0, 1), a2 + hstepA, voffA);
;             PG8_WAIT_V(8); PG8_WAIT_L(0); PG8_BAR; PG8_MMA(0, 0, At, B0); PG8_MMA(0, 1, At, B1); PG8_BAR; PG8_SCHED;
;             PG8_LDA(At, 1, 1); PG8_STAGE_NT(PG8_SB(1, 0), b3, voffB); PG8_STAGE_NT(PG8_SB(1, 1), b3 + hstepB, voffB); PG8_STAGE(PG8_SA(1, 0), a3, voffA);
;             PG8_WAIT_V(8); PG8_WAIT_L(0); PG8_BAR; PG8_MMA(1, 0, At, B0); PG8_MMA(1, 1, At, B1); PG8_BAR; PG8_SCHED;
	s_add_i32 s65, 0, 0x18000
	v_add_u32_e32 v140, s65, v203
	s_add_i32 s66, 0, 0x1c000
	ds_read_b128 v[128:131], v140
	ds_read_b128 v[132:135], v140 offset:1024
	ds_read_b128 v[136:139], v140 offset:2048
	ds_read_b128 v[140:143], v140 offset:3072
	v_add_u32_e32 v156, s66, v203
	ds_read_b128 v[144:147], v156
	ds_read_b128 v[148:151], v156 offset:1024
	ds_read_b128 v[152:155], v156 offset:2048
	ds_read_b128 v[156:159], v156 offset:3072
	s_add_u32 s46, s52, 0x2b4000
	s_addc_u32 s47, s53, 0
	s_mov_b32 m0, s23
	ds_read_b128 v[160:163], v207 offset:32768
	ds_read_b128 v[164:167], v207 offset:33792
	ds_read_b128 v[184:187], v207 offset:34816
	ds_read_b128 v[188:191], v207 offset:35840
	ds_read_b128 v[192:195], v207 offset:36864
	ds_read_b128 v[196:199], v207 offset:37888
	ds_read_b128 v[210:213], v207 offset:38912
	ds_read_b128 v[214:217], v207 offset:39936
	global_load_lds_dwordx4 v168, s[46:47]
	s_mov_b32 m0, s24
	s_nop 0
	global_load_lds_dwordx4 v172, s[46:47]
	s_mov_b32 m0, s19
	s_nop 0
	global_load_lds_dwordx4 v168, s[52:53]
	s_mov_b32 m0, s22
	s_nop 0
	global_load_lds_dwordx4 v172, s[52:53]
	s_nop 0
	s_waitcnt vmcnt(8) lgkmcnt(0)
	s_barrier
	v_mfma_f32_16x16x32_bf16 v[124:127], v[128:131], v[160:163], v[124:127]
	v_mfma_f32_16x16x32_bf16 v[120:123], v[136:139], v[160:163], v[120:123]
	v_mfma_f32_16x16x32_bf16 v[116:119], v[128:131], v[184:187], v[116:119]
	v_mfma_f32_16x16x32_bf16 v[112:115], v[136:139], v[184:187], v[112:115]
	v_mfma_f32_16x16x32_bf16 v[92:95], v[128:131], v[192:195], v[92:95]
	v_mfma_f32_16x16x32_bf16 v[88:91], v[136:139], v[192:195], v[88:91]
	v_mfma_f32_16x16x32_bf16 v[76:79], v[128:131], v[210:213], v[76:79]
	v_mfma_f32_16x16x32_bf16 v[72:75], v[136:139], v[210:213], v[72:75]
	v_mfma_f32_16x16x32_bf16 v[124:127], v[132:135], v[164:167], v[124:127]
	v_mfma_f32_16x16x32_bf16 v[120:123], v[140:143], v[164:167], v[120:123]
	v_mfma_f32_16x16x32_bf16 v[116:119], v[132:135], v[188:191], v[116:119]
	v_mfma_f32_16x16x32_bf16 v[112:115], v[140:143], v[188:191], v[112:115]
	v_mfma_f32_16x16x32_bf16 v[92:95], v[132:135], v[196:199], v[92:95]
	v_mfma_f32_16x16x32_bf16 v[88:91], v[140:143], v[196:199], v[88:91]
	v_mfma_f32_16x16x32_bf16 v[76:79], v[132:135], v[214:217], v[76:79]
	v_mfma_f32_16x16x32_bf16 v[72:75], v[140:143], v[214:217], v[72:75]
	v_mfma_f32_16x16x32_bf16 v[108:111], v[144:147], v[160:163], v[108:111]
	v_mfma_f32_16x16x32_bf16 v[104:107], v[152:155], v[160:163], v[104:107]
	v_mfma_f32_16x16x32_bf16 v[100:103], v[144:147], v[184:187], v[100:103]
	v_mfma_f32_16x16x32_bf16 v[96:99], v[152:155], v[184:187], v[96:99]
	v_mfma_f32_16x16x32_bf16 v[84:87], v[144:147], v[192:195], v[84:87]
	v_mfma_f32_16x16x32_bf16 v[80:83], v[152:155], v[192:195], v[80:83]
	v_mfma_f32_16x16x32_bf16 v[68:71], v[144:147], v[210:213], v[68:71]
	v_mfma_f32_16x16x32_bf16 v[64:67], v[152:155], v[210:213], v[64:67]
	v_mfma_f32_16x16x32_bf16 v[108:111], v[148:151], v[164:167], v[108:111]
	v_mfma_f32_16x16x32_bf16 v[104:107], v[156:159], v[164:167], v[104:107]
	v_mfma_f32_16x16x32_bf16 v[100:103], v[148:151], v[188:191], v[100:103]
	v_mfma_f32_16x16x32_bf16 v[96:99], v[156:159], v[188:191], v[96:99]
	v_mfma_f32_16x16x32_bf16 v[84:87], v[148:151], v[196:199], v[84:87]
	v_mfma_f32_16x16x32_bf16 v[80:83], v[156:159], v[196:199], v[80:83]
	v_mfma_f32_16x16x32_bf16 v[68:71], v[148:151], v[214:217], v[68:71]
	v_mfma_f32_16x16x32_bf16 v[64:67], v[156:159], v[214:217], v[64:67]
	s_barrier
	s_add_i32 s46, s65, s17
	s_mov_b32 m0, s46
	s_add_u32 s98, s50, 0x80
	s_addc_u32 s99, s51, 0
	ds_read_b128 v[160:163], v207 offset:49152
	ds_read_b128 v[164:167], v207 offset:50176
	ds_read_b128 v[184:187], v207 offset:51200
	ds_read_b128 v[188:191], v207 offset:52224
	ds_read_b128 v[192:195], v207 offset:53248
	ds_read_b128 v[196:199], v207 offset:54272
	ds_read_b128 v[210:213], v207 offset:55296
	ds_read_b128 v[214:217], v207 offset:56320
	global_load_lds_dwordx4 v170, s[98:99]
	s_add_i32 m0, s46, 0x2000
	s_add_u32 s46, s50, 0x2b4080
	s_addc_u32 s47, s51, 0
	s_add_i32 s50, s66, s17
	global_load_lds_dwordx4 v174, s[98:99]
	s_mov_b32 m0, s50
	s_nop 0
	global_load_lds_dwordx4 v170, s[46:47]
	s_add_i32 m0, s50, 0x2000
	s_nop 0
	global_load_lds_dwordx4 v174, s[46:47]
	s_nop 0
	s_waitcnt vmcnt(4) lgkmcnt(0)
	s_barrier
	v_mfma_f32_16x16x32_bf16 v[60:63], v[128:131], v[160:163], v[60:63]
	v_mfma_f32_16x16x32_bf16 v[56:59], v[136:139], v[160:163], v[56:59]
	v_mfma_f32_16x16x32_bf16 v[44:47], v[128:131], v[184:187], v[44:47]
	v_mfma_f32_16x16x32_bf16 v[40:43], v[136:139], v[184:187], v[40:43]
	v_mfma_f32_16x16x32_bf16 v[28:31], v[128:131], v[192:195], v[28:31]
	v_mfma_f32_16x16x32_bf16 v[24:27], v[136:139], v[192:195], v[24:27]
	v_mfma_f32_16x16x32_bf16 v[12:15], v[128:131], v[210:213], v[12:15]
	v_mfma_f32_16x16x32_bf16 v[8:11], v[136:139], v[210:213], v[8:11]
	v_mfma_f32_16x16x32_bf16 v[60:63], v[132:135], v[164:167], v[60:63]
	v_mfma_f32_16x16x32_bf16 v[56:59], v[140:143], v[164:167], v[56:59]
	v_mfma_f32_16x16x32_bf16 v[44:47], v[132:135], v[188:191], v[44:47]
	v_mfma_f32_16x16x32_bf16 v[40:43], v[140:143], v[188:191], v[40:43]
	v_mfma_f32_16x16x32_bf16 v[28:31], v[132:135], v[196:199], v[28:31]
	v_mfma_f32_16x16x32_bf16 v[24:27], v[140:143], v[196:199], v[24:27]
	v_mfma_f32_16x16x32_bf16 v[12:15], v[132:135], v[214:217], v[12:15]
	v_mfma_f32_16x16x32_bf16 v[8:11], v[140:143], v[214:217], v[8:11]
	v_mfma_f32_16x16x32_bf16 v[52:55], v[144:147], v[160:163], v[52:55]
	v_mfma_f32_16x16x32_bf16 v[48:51], v[152:155], v[160:163], v[48:51]
	v_mfma_f32_16x16x32_bf16 v[36:39], v[144:147], v[184:187], v[36:39]
	v_mfma_f32_16x16x32_bf16 v[32:35], v[152:155], v[184:187], v[32:35]
	v_mfma_f32_16x16x32_bf16 v[20:23], v[144:147], v[192:195], v[20:23]
	v_mfma_f32_16x16x32_bf16 v[16:19], v[152:155], v[192:195], v[16:19]
	v_mfma_f32_16x16x32_bf16 v[4:7], v[144:147], v[210:213], v[4:7]
	v_mfma_f32_16x16x32_bf16 v[0:3], v[152:155], v[210:213], v[0:3]
	v_mfma_f32_16x16x32_bf16 v[52:55], v[148:151], v[164:167], v[52:55]
	v_mfma_f32_16x16x32_bf16 v[48:51], v[156:159], v[164:167], v[48:51]
	v_mfma_f32_16x16x32_bf16 v[36:39], v[148:151], v[188:191], v[36:39]
	v_mfma_f32_16x16x32_bf16 v[32:35], v[156:159], v[188:191], v[32:35]
	v_mfma_f32_16x16x32_bf16 v[20:23], v[148:151], v[196:199], v[20:23]
	v_mfma_f32_16x16x32_bf16 v[16:19], v[156:159], v[196:199], v[16:19]
	v_mfma_f32_16x16x32_bf16 v[4:7], v[148:151], v[214:217], v[4:7]
	v_mfma_f32_16x16x32_bf16 v[0:3], v[156:159], v[214:217], v[0:3]
	s_barrier
	s_add_i32 s64, s64, 2
	s_add_u32 s62, s62, 0x100
	s_addc_u32 s63, s63, 0
	s_cmpk_gt_u32 s64, 0xa9
	s_mov_b64 s[46:47], s[48:49]
	s_cbranch_scc0 .LBB0_317
	s_and_b64 vcc, exec, s[42:43]
	s_cbranch_vccz .LBB0_320
	s_barrier

; #define PG8_STAGE(bufoff, gbase, voff) do { _Pragma("unroll") for (int _i = 0; _i < 2; ++_i) \
;         __builtin_amdgcn_global_load_lds((const unsigned*)((const char*)(gbase) + (voff)[_i]), (PG8_LAS unsigned*)(lds + (bufoff) + ldsw + _i * 8192), 16, 0, 0); } while (0)
; #define PG8_STAGE_NT(bufoff, gbase, voff) do { _Pragma("unroll") for (int _i = 0; _i < 2; ++_i) \
;         __builtin_amdgcn_global_load_lds((const unsigned*)((const char*)(gbase) + (voff)[_i]), (PG8_LAS unsigned*)(lds + (bufoff) + ldsw + _i * 8192), 16, 0, PG8_B_AUX); } while (0)
; #define PG8_LDA(dst, b, h) do { _Pragma("unroll") for (int m = 0; m < 4; ++m) _Pragma("unroll") for (int k = 0; k < 2; ++k) dst[m][k] = *(const PG8_LAS bf16x8*)(lds + PG8_SA(b, h) + aoff + m * 2048 + k * 1024); } while (0)
; #define PG8_LDB(dst, b, h) do { _Pragma("unroll") for (int n = 0; n < 2; ++n) _Pragma("unroll") for (int k = 0; k < 2; ++k) dst[n][k] = *(const PG8_LAS bf16x8*)(lds + PG8_SB(b, h) + boff + n * 2048 + k * 1024); } while (0)
; #define PG8_WAIT_V(n) asm volatile("s_waitcnt vmcnt(" #n ")" ::: "memory")
; #define PG8_WAIT_L(n) asm volatile("s_waitcnt lgkmcnt(" #n ")" ::: "memory")
; #define PG8_BAR __builtin_amdgcn_s_barrier()
; #define PG8_SCHED __builtin_amdgcn_sched_barrier(0)
; template <class Epi, class Sched, bool ALIGN_EPI = false, bool SP2 = false>
; __device__ __forceinline__ void gemm_phase(PG8_LAS unsigned char* lds, const Gemm g, const Sched& S, const Epi& E, int wid) {
;     ...
;             const bool last = (t == nt - 2);
;             const char* a1 = cA + (size_t)(t + 1) * kstep;
;             const char* a2 = last ? nA : cA + (size_t)(t + 2) * kstep; const char* b2 = last ? nB : cB + (size_t)(t + 2) * kstep;
;             const char* a3 = a2 + kstep; const char* b3 = b2 + kstep;
;             if (last && has_next) S.a_ready(nxt);
;             if constexpr (SP2) {
;             PG8_LDB(B0, 0, 0); PG8_LDB(B1, 0, 1); PG8_SCHED; PG8_LDA(At, 0, 0); PG8_STAGE(PG8_SA(1, 1), a1 + hstepA, voffA);
;             PG8_WAIT_V(8); PG8_WAIT_L(0); PG8_BAR; PG8_MMA(0, 0, At, B0); PG8_MMA(0, 1, At, B1); PG8_BAR; PG8_SCHED;
;             PG8_LDA(At, 0, 1); PG8_STAGE_NT(PG8_SB(0, 0), b2, voffB); PG8_STAGE_NT(PG8_SB(0, 1), b2 + hstepB, voffB); PG8_STAGE(PG8_SA(0, 0), a2, voffA);
;             PG8_WAIT_V(8); PG8_WAIT_L(0); PG8_BAR; PG8_MMA(1, 0, At, B0); PG8_MMA(1, 1, At, B1); PG8_BAR; PG8_SCHED;
.LBB0_426:
	ds_read_b128 v[144:147], v161
	ds_read_b128 v[148:151], v161 offset:1024
	ds_read_b128 v[152:155], v161 offset:2048
	ds_read_b128 v[166:169], v161 offset:3072
	ds_read_b128 v[170:173], v162
	ds_read_b128 v[174:177], v162 offset:1024
	ds_read_b128 v[178:181], v162 offset:2048
	ds_read_b128 v[182:185], v162 offset:3072
	s_add_u32 s4, s46, 0x100
	s_addc_u32 s5, s47, 0
	s_add_u32 s98, s46, 0x80
	s_addc_u32 s99, s47, 0
	s_add_u32 s100, s46, 0x104080
	s_addc_u32 s101, s47, 0
	s_cmp_eq_u32 s64, 60
	s_cselect_b32 s51, s43, s5
	s_cselect_b32 s50, s42, s4
	s_cselect_b32 s49, s45, s63
	s_cselect_b32 s48, s44, s62
	s_add_i32 m0, s23, 0xc000
	ds_read_b128 v[186:189], v163
	ds_read_b128 v[190:193], v163 offset:1024
	ds_read_b128 v[194:197], v163 offset:2048
	ds_read_b128 v[198:201], v163 offset:3072
	ds_read_b128 v[202:205], v163 offset:4096
	ds_read_b128 v[206:209], v163 offset:5120
	ds_read_b128 v[210:213], v163 offset:6144
	ds_read_b128 v[214:217], v163 offset:7168
	global_load_lds_dwordx4 v134, s[100:101]
	s_add_i32 m0, s23, 0xe000
	s_nop 0
	global_load_lds_dwordx4 v130, s[100:101]
	s_mov_b32 m0, s53
	s_nop 0
	global_load_lds_dwordx4 v134, s[98:99]
	s_mov_b32 m0, s54
	s_nop 0
	global_load_lds_dwordx4 v130, s[98:99]
	s_waitcnt vmcnt(8) lgkmcnt(0)
	s_barrier
	v_mfma_f32_16x16x32_bf16 v[124:127], v[144:147], v[186:189], v[124:127]
	v_mfma_f32_16x16x32_bf16 v[120:123], v[152:155], v[186:189], v[120:123]
	v_mfma_f32_16x16x32_bf16 v[116:119], v[144:147], v[194:197], v[116:119]
	v_mfma_f32_16x16x32_bf16 v[112:115], v[152:155], v[194:197], v[112:115]
	v_mfma_f32_16x16x32_bf16 v[92:95], v[144:147], v[202:205], v[92:95]
	v_mfma_f32_16x16x32_bf16 v[88:91], v[152:155], v[202:205], v[88:91]
	v_mfma_f32_16x16x32_bf16 v[76:79], v[144:147], v[210:213], v[76:79]
	v_mfma_f32_16x16x32_bf16 v[72:75], v[152:155], v[210:213], v[72:75]
	v_mfma_f32_16x16x32_bf16 v[124:127], v[148:151], v[190:193], v[124:127]
	v_mfma_f32_16x16x32_bf16 v[120:123], v[166:169], v[190:193], v[120:123]
	v_mfma_f32_16x16x32_bf16 v[116:119], v[148:151], v[198:201], v[116:119]
	v_mfma_f32_16x16x32_bf16 v[112:115], v[166:169], v[198:201], v[112:115]
	v_mfma_f32_16x16x32_bf16 v[92:95], v[148:151], v[206:209], v[92:95]
	v_mfma_f32_16x16x32_bf16 v[88:91], v[166:169], v[206:209], v[88:91]
	v_mfma_f32_16x16x32_bf16 v[76:79], v[148:151], v[214:217], v[76:79]
	v_mfma_f32_16x16x32_bf16 v[72:75], v[166:169], v[214:217], v[72:75]
	v_mfma_f32_16x16x32_bf16 v[108:111], v[170:173], v[186:189], v[108:111]
	v_mfma_f32_16x16x32_bf16 v[104:107], v[178:181], v[186:189], v[104:107]
	v_mfma_f32_16x16x32_bf16 v[100:103], v[170:173], v[194:197], v[100:103]
	v_mfma_f32_16x16x32_bf16 v[96:99], v[178:181], v[194:197], v[96:99]
	v_mfma_f32_16x16x32_bf16 v[84:87], v[170:173], v[202:205], v[84:87]
	v_mfma_f32_16x16x32_bf16 v[80:83], v[178:181], v[202:205], v[80:83]
	v_mfma_f32_16x16x32_bf16 v[68:71], v[170:173], v[210:213], v[68:71]
	v_mfma_f32_16x16x32_bf16 v[64:67], v[178:181], v[210:213], v[64:67]
	v_mfma_f32_16x16x32_bf16 v[108:111], v[174:177], v[190:193], v[108:111]
	v_mfma_f32_16x16x32_bf16 v[104:107], v[182:185], v[190:193], v[104:107]
	v_mfma_f32_16x16x32_bf16 v[100:103], v[174:177], v[198:201], v[100:103]
	v_mfma_f32_16x16x32_bf16 v[96:99], v[182:185], v[198:201], v[96:99]
	v_mfma_f32_16x16x32_bf16 v[84:87], v[174:177], v[206:209], v[84:87]
	v_mfma_f32_16x16x32_bf16 v[80:83], v[182:185], v[206:209], v[80:83]
	v_mfma_f32_16x16x32_bf16 v[68:71], v[174:177], v[214:217], v[68:71]
	v_mfma_f32_16x16x32_bf16 v[64:67], v[182:185], v[214:217], v[64:67]
	s_barrier
	s_add_i32 s46, s56, s17
	s_mov_b32 m0, s46
	ds_read_b128 v[186:189], v163 offset:16384
	ds_read_b128 v[190:193], v163 offset:17408
	ds_read_b128 v[194:197], v163 offset:18432
	ds_read_b128 v[198:201], v163 offset:19456
	ds_read_b128 v[202:205], v163 offset:20480
	ds_read_b128 v[206:209], v163 offset:21504
	ds_read_b128 v[210:213], v163 offset:22528
	ds_read_b128 v[214:217], v163 offset:23552
	global_load_lds_dwordx4 v132, s[48:49]
	s_add_i32 m0, s46, 0x2000
	s_add_u32 s46, s48, 0x104000
	s_addc_u32 s47, s49, 0
	s_add_i32 s65, s57, s17
	global_load_lds_dwordx4 v128, s[48:49]
	s_mov_b32 m0, s65
	s_nop 0
	global_load_lds_dwordx4 v132, s[46:47]
	s_add_i32 m0, s65, 0x2000
	s_nop 0
	global_load_lds_dwordx4 v128, s[46:47]
	s_waitcnt vmcnt(4) lgkmcnt(0)
	s_barrier
	v_mfma_f32_16x16x32_bf16 v[60:63], v[144:147], v[186:189], v[60:63]
	v_mfma_f32_16x16x32_bf16 v[56:59], v[152:155], v[186:189], v[56:59]
	v_mfma_f32_16x16x32_bf16 v[44:47], v[144:147], v[194:197], v[44:47]
	v_mfma_f32_16x16x32_bf16 v[40:43], v[152:155], v[194:197], v[40:43]
	v_mfma_f32_16x16x32_bf16 v[28:31], v[144:147], v[202:205], v[28:31]
	v_mfma_f32_16x16x32_bf16 v[24:27], v[152:155], v[202:205], v[24:27]
	v_mfma_f32_16x16x32_bf16 v[12:15], v[144:147], v[210:213], v[12:15]
	v_mfma_f32_16x16x32_bf16 v[8:11], v[152:155], v[210:213], v[8:11]
	v_mfma_f32_16x16x32_bf16 v[60:63], v[148:151], v[190:193], v[60:63]
	v_mfma_f32_16x16x32_bf16 v[56:59], v[166:169], v[190:193], v[56:59]
	v_mfma_f32_16x16x32_bf16 v[44:47], v[148:151], v[198:201], v[44:47]
	v_mfma_f32_16x16x32_bf16 v[40:43], v[166:169], v[198:201], v[40:43]
	v_mfma_f32_16x16x32_bf16 v[28:31], v[148:151], v[206:209], v[28:31]
	v_mfma_f32_16x16x32_bf16 v[24:27], v[166:169], v[206:209], v[24:27]
	v_mfma_f32_16x16x32_bf16 v[12:15], v[148:151], v[214:217], v[12:15]
	v_mfma_f32_16x16x32_bf16 v[8:11], v[166:169], v[214:217], v[8:11]
	v_mfma_f32_16x16x32_bf16 v[52:55], v[170:173], v[186:189], v[52:55]
	v_mfma_f32_16x16x32_bf16 v[48:51], v[178:181], v[186:189], v[48:51]
	v_mfma_f32_16x16x32_bf16 v[36:39], v[170:173], v[194:197], v[36:39]
	v_mfma_f32_16x16x32_bf16 v[32:35], v[178:181], v[194:197], v[32:35]
	v_mfma_f32_16x16x32_bf16 v[20:23], v[170:173], v[202:205], v[20:23]
	v_mfma_f32_16x16x32_bf16 v[16:19], v[178:181], v[202:205], v[16:19]
	v_mfma_f32_16x16x32_bf16 v[4:7], v[170:173], v[210:213], v[4:7]
	v_mfma_f32_16x16x32_bf16 v[0:3], v[178:181], v[210:213], v[0:3]
	v_mfma_f32_16x16x32_bf16 v[52:55], v[174:177], v[190:193], v[52:55]
	v_mfma_f32_16x16x32_bf16 v[48:51], v[182:185], v[190:193], v[48:51]
	v_mfma_f32_16x16x32_bf16 v[36:39], v[174:177], v[198:201], v[36:39]
	v_mfma_f32_16x16x32_bf16 v[32:35], v[182:185], v[198:201], v[32:35]
	v_mfma_f32_16x16x32_bf16 v[20:23], v[174:177], v[206:209], v[20:23]
	v_mfma_f32_16x16x32_bf16 v[16:19], v[182:185], v[206:209], v[16:19]
	v_mfma_f32_16x16x32_bf16 v[4:7], v[174:177], v[214:217], v[4:7]
	v_mfma_f32_16x16x32_bf16 v[0:3], v[182:185], v[214:217], v[0:3]
	s_barrier
; #define PG8_STAGE(bufoff, gbase, voff) do { _Pragma("unroll") for (int _i = 0; _i < 2; ++_i) \
;         __builtin_amdgcn_global_load_lds((const unsigned*)((const char*)(gbase) + (voff)[_i]), (PG8_LAS unsigned*)(lds + (bufoff) + ldsw + _i * 8192), 16, 0, 0); } while (0)
; #define PG8_STAGE_NT(bufoff, gbase, voff) do { _Pragma("unroll") for (int _i = 0; _i < 2; ++_i) \
;         __builtin_amdgcn_global_load_lds((const unsigned*)((const char*)(gbase) + (voff)[_i]), (PG8_LAS unsigned*)(lds + (bufoff) + ldsw + _i * 8192), 16, 0, PG8_B_AUX); } while (0)
; #define PG8_LDA(dst, b, h) do { _Pragma("unroll") for (int m = 0; m < 4; ++m) _Pragma("unroll") for (int k = 0; k < 2; ++k) dst[m][k] = *(const PG8_LAS bf16x8*)(lds + PG8_SA(b, h) + aoff + m * 2048 + k * 1024); } while (0)
; #define PG8_LDB(dst, b, h) do { _Pragma("unroll") for (int n = 0; n < 2; ++n) _Pragma("unroll") for (int k = 0; k < 2; ++k) dst[n][k] = *(const PG8_LAS bf16x8*)(lds + PG8_SB(b, h) + boff + n * 2048 + k * 1024); } while (0)
; #define PG8_MMA(ai, bj, At, Bt) do { __builtin_amdgcn_s_setprio(1); _Pragma("unroll") for (int m = 0; m < 4; ++m) _Pragma("unroll") for (int n = 0; n < 2; ++n) _Pragma("unroll") for (int k = 0; k < 2; ++k) \
;         acc[ai][bj][m][n] = __builtin_amdgcn_mfma_f32_16x16x32_bf16(Bt[n][k], At[m][k], acc[ai][bj][m][n], 0, 0, 0); __builtin_amdgcn_s_setprio(0); } while (0)
; #define PG8_WAIT_V(n) asm volatile("s_waitcnt vmcnt(" #n ")" ::: "memory")
; #define PG8_WAIT_L(n) asm volatile("s_waitcnt lgkmcnt(" #n ")" ::: "memory")
; #define PG8_BAR __builtin_amdgcn_s_barrier()
; #define PG8_SCHED __builtin_amdgcn_sched_barrier(0)
; template <class Epi, class Sched, bool ALIGN_EPI = false, bool SP2 = false>
; __device__ __forceinline__ void gemm_phase(PG8_LAS unsigned char* lds, const Gemm g, const Sched& S, const Epi& E, int wid) {
;     ...
;             PG8_LDB(B0, 1, 0); PG8_LDB(B1, 1, 1); PG8_SCHED; PG8_LDA(At, 1, 0); PG8_STAGE(PG8_SA(0, 1), a2 + hstepA, voffA);
;             PG8_WAIT_V(8); PG8_WAIT_L(0); PG8_BAR; PG8_MMA(0, 0, At, B0); PG8_MMA(0, 1, At, B1); PG8_BAR; PG8_SCHED;
;             PG8_LDA(At, 1, 1); PG8_STAGE_NT(PG8_SB(1, 0), b3, voffB); PG8_STAGE_NT(PG8_SB(1, 1), b3 + hstepB, voffB); PG8_STAGE(PG8_SA(1, 0), a3, voffA);
;             PG8_WAIT_V(8); PG8_WAIT_L(0); PG8_BAR; PG8_MMA(1, 0, At, B0); PG8_MMA(1, 1, At, B1); PG8_BAR; PG8_SCHED;
	s_add_i32 s65, 0, 0x18000
	v_add_u32_e32 v165, s65, v159
	s_add_i32 s66, 0, 0x1c000
	ds_read_b128 v[144:147], v165
	ds_read_b128 v[148:151], v165 offset:1024
	ds_read_b128 v[152:155], v165 offset:2048
	ds_read_b128 v[166:169], v165 offset:3072
	v_add_u32_e32 v165, s66, v159
	ds_read_b128 v[170:173], v165
	ds_read_b128 v[174:177], v165 offset:1024
	ds_read_b128 v[178:181], v165 offset:2048
	ds_read_b128 v[182:185], v165 offset:3072
	s_add_u32 s46, s50, 0x104000
	s_addc_u32 s47, s51, 0
	s_mov_b32 m0, s25
	ds_read_b128 v[186:189], v163 offset:32768
	ds_read_b128 v[190:193], v163 offset:33792
	ds_read_b128 v[194:197], v163 offset:34816
	ds_read_b128 v[198:201], v163 offset:35840
	ds_read_b128 v[202:205], v163 offset:36864
	ds_read_b128 v[206:209], v163 offset:37888
	ds_read_b128 v[210:213], v163 offset:38912
	ds_read_b128 v[214:217], v163 offset:39936
	global_load_lds_dwordx4 v134, s[46:47]
	s_mov_b32 m0, s29
	s_nop 0
	global_load_lds_dwordx4 v130, s[46:47]
	s_mov_b32 m0, s23
	s_nop 0
	global_load_lds_dwordx4 v134, s[50:51]
	s_mov_b32 m0, s24
	s_nop 0
	global_load_lds_dwordx4 v130, s[50:51]
	s_nop 0
	s_waitcnt vmcnt(8) lgkmcnt(0)
	s_barrier
	v_mfma_f32_16x16x32_bf16 v[124:127], v[144:147], v[186:189], v[124:127]
	v_mfma_f32_16x16x32_bf16 v[120:123], v[152:155], v[186:189], v[120:123]
	v_mfma_f32_16x16x32_bf16 v[116:119], v[144:147], v[194:197], v[116:119]
	v_mfma_f32_16x16x32_bf16 v[112:115], v[152:155], v[194:197], v[112:115]
	v_mfma_f32_16x16x32_bf16 v[92:95], v[144:147], v[202:205], v[92:95]
	v_mfma_f32_16x16x32_bf16 v[88:91], v[152:155], v[202:205], v[88:91]
	v_mfma_f32_16x16x32_bf16 v[76:79], v[144:147], v[210:213], v[76:79]
	v_mfma_f32_16x16x32_bf16 v[72:75], v[152:155], v[210:213], v[72:75]
	v_mfma_f32_16x16x32_bf16 v[124:127], v[148:151], v[190:193], v[124:127]
	v_mfma_f32_16x16x32_bf16 v[120:123], v[166:169], v[190:193], v[120:123]
	v_mfma_f32_16x16x32_bf16 v[116:119], v[148:151], v[198:201], v[116:119]
	v_mfma_f32_16x16x32_bf16 v[112:115], v[166:169], v[198:201], v[112:115]
	v_mfma_f32_16x16x32_bf16 v[92:95], v[148:151], v[206:209], v[92:95]
	v_mfma_f32_16x16x32_bf16 v[88:91], v[166:169], v[206:209], v[88:91]
	v_mfma_f32_16x16x32_bf16 v[76:79], v[148:151], v[214:217], v[76:79]
	v_mfma_f32_16x16x32_bf16 v[72:75], v[166:169], v[214:217], v[72:75]
	v_mfma_f32_16x16x32_bf16 v[108:111], v[170:173], v[186:189], v[108:111]
	v_mfma_f32_16x16x32_bf16 v[104:107], v[178:181], v[186:189], v[104:107]
	v_mfma_f32_16x16x32_bf16 v[100:103], v[170:173], v[194:197], v[100:103]
	v_mfma_f32_16x16x32_bf16 v[96:99], v[178:181], v[194:197], v[96:99]
	v_mfma_f32_16x16x32_bf16 v[84:87], v[170:173], v[202:205], v[84:87]
	v_mfma_f32_16x16x32_bf16 v[80:83], v[178:181], v[202:205], v[80:83]
	v_mfma_f32_16x16x32_bf16 v[68:71], v[170:173], v[210:213], v[68:71]
	v_mfma_f32_16x16x32_bf16 v[64:67], v[178:181], v[210:213], v[64:67]
	v_mfma_f32_16x16x32_bf16 v[108:111], v[174:177], v[190:193], v[108:111]
	v_mfma_f32_16x16x32_bf16 v[104:107], v[182:185], v[190:193], v[104:107]
	v_mfma_f32_16x16x32_bf16 v[100:103], v[174:177], v[198:201], v[100:103]
	v_mfma_f32_16x16x32_bf16 v[96:99], v[182:185], v[198:201], v[96:99]
	v_mfma_f32_16x16x32_bf16 v[84:87], v[174:177], v[206:209], v[84:87]
	v_mfma_f32_16x16x32_bf16 v[80:83], v[182:185], v[206:209], v[80:83]
	v_mfma_f32_16x16x32_bf16 v[68:71], v[174:177], v[214:217], v[68:71]
	v_mfma_f32_16x16x32_bf16 v[64:67], v[182:185], v[214:217], v[64:67]
	s_barrier
	s_add_i32 s46, s65, s17
	s_mov_b32 m0, s46
	s_add_u32 s98, s48, 0x80
	s_addc_u32 s99, s49, 0
	ds_read_b128 v[186:189], v163 offset:49152
	ds_read_b128 v[190:193], v163 offset:50176
	ds_read_b128 v[194:197], v163 offset:51200
	ds_read_b128 v[198:201], v163 offset:52224
	ds_read_b128 v[202:205], v163 offset:53248
	ds_read_b128 v[206:209], v163 offset:54272
	ds_read_b128 v[210:213], v163 offset:55296
	ds_read_b128 v[214:217], v163 offset:56320
	global_load_lds_dwordx4 v132, s[98:99]
	s_add_i32 m0, s46, 0x2000
	s_add_u32 s46, s48, 0x104080
	s_addc_u32 s47, s49, 0
	s_add_i32 s48, s66, s17
	global_load_lds_dwordx4 v128, s[98:99]
	s_mov_b32 m0, s48
	s_nop 0
	global_load_lds_dwordx4 v132, s[46:47]
	s_add_i32 m0, s48, 0x2000
	s_nop 0
	global_load_lds_dwordx4 v128, s[46:47]
	s_nop 0
	s_waitcnt vmcnt(4) lgkmcnt(0)
	s_barrier
	v_mfma_f32_16x16x32_bf16 v[60:63], v[144:147], v[186:189], v[60:63]
	v_mfma_f32_16x16x32_bf16 v[56:59], v[152:155], v[186:189], v[56:59]
	v_mfma_f32_16x16x32_bf16 v[44:47], v[144:147], v[194:197], v[44:47]
	v_mfma_f32_16x16x32_bf16 v[40:43], v[152:155], v[194:197], v[40:43]
	v_mfma_f32_16x16x32_bf16 v[28:31], v[144:147], v[202:205], v[28:31]
	v_mfma_f32_16x16x32_bf16 v[24:27], v[152:155], v[202:205], v[24:27]
	v_mfma_f32_16x16x32_bf16 v[12:15], v[144:147], v[210:213], v[12:15]
	v_mfma_f32_16x16x32_bf16 v[8:11], v[152:155], v[210:213], v[8:11]
	v_mfma_f32_16x16x32_bf16 v[60:63], v[148:151], v[190:193], v[60:63]
	v_mfma_f32_16x16x32_bf16 v[56:59], v[166:169], v[190:193], v[56:59]
	v_mfma_f32_16x16x32_bf16 v[44:47], v[148:151], v[198:201], v[44:47]
	v_mfma_f32_16x16x32_bf16 v[40:43], v[166:169], v[198:201], v[40:43]
	v_mfma_f32_16x16x32_bf16 v[28:31], v[148:151], v[206:209], v[28:31]
	v_mfma_f32_16x16x32_bf16 v[24:27], v[166:169], v[206:209], v[24:27]
	v_mfma_f32_16x16x32_bf16 v[12:15], v[148:151], v[214:217], v[12:15]
	v_mfma_f32_16x16x32_bf16 v[8:11], v[166:169], v[214:217], v[8:11]
	v_mfma_f32_16x16x32_bf16 v[52:55], v[170:173], v[186:189], v[52:55]
	v_mfma_f32_16x16x32_bf16 v[48:51], v[178:181], v[186:189], v[48:51]
	v_mfma_f32_16x16x32_bf16 v[36:39], v[170:173], v[194:197], v[36:39]
	v_mfma_f32_16x16x32_bf16 v[32:35], v[178:181], v[194:197], v[32:35]
	v_mfma_f32_16x16x32_bf16 v[20:23], v[170:173], v[202:205], v[20:23]
	v_mfma_f32_16x16x32_bf16 v[16:19], v[178:181], v[202:205], v[16:19]
	v_mfma_f32_16x16x32_bf16 v[4:7], v[170:173], v[210:213], v[4:7]
	v_mfma_f32_16x16x32_bf16 v[0:3], v[178:181], v[210:213], v[0:3]
	v_mfma_f32_16x16x32_bf16 v[52:55], v[174:177], v[190:193], v[52:55]
	v_mfma_f32_16x16x32_bf16 v[48:51], v[182:185], v[190:193], v[48:51]
	v_mfma_f32_16x16x32_bf16 v[36:39], v[174:177], v[198:201], v[36:39]
	v_mfma_f32_16x16x32_bf16 v[32:35], v[182:185], v[198:201], v[32:35]
	v_mfma_f32_16x16x32_bf16 v[20:23], v[174:177], v[206:209], v[20:23]
	v_mfma_f32_16x16x32_bf16 v[16:19], v[182:185], v[206:209], v[16:19]
	v_mfma_f32_16x16x32_bf16 v[4:7], v[174:177], v[214:217], v[4:7]
	v_mfma_f32_16x16x32_bf16 v[0:3], v[182:185], v[214:217], v[0:3]
	s_barrier
	s_add_i32 s64, s64, 2
	s_add_u32 s62, s62, 0x100
	s_addc_u32 s63, s63, 0
	s_cmp_gt_u32 s64, 61
	s_mov_b64 s[46:47], s[4:5]
	s_cbranch_scc0 .LBB0_426
	s_and_b64 vcc, exec, s[40:41]
	s_cbranch_vccz .LBB0_429
	s_barrier

; #define PG8_STAGE(bufoff, gbase, voff) do { _Pragma("unroll") for (int _i = 0; _i < 2; ++_i) \
;         __builtin_amdgcn_global_load_lds((const unsigned*)((const char*)(gbase) + (voff)[_i]), (PG8_LAS unsigned*)(lds + (bufoff) + ldsw + _i * 8192), 16, 0, 0); } while (0)
; #define PG8_STAGE_NT(bufoff, gbase, voff) do { _Pragma("unroll") for (int _i = 0; _i < 2; ++_i) \
;         __builtin_amdgcn_global_load_lds((const unsigned*)((const char*)(gbase) + (voff)[_i]), (PG8_LAS unsigned*)(lds + (bufoff) + ldsw + _i * 8192), 16, 0, PG8_B_AUX); } while (0)
; #define PG8_LDA(dst, b, h) do { _Pragma("unroll") for (int m = 0; m < 4; ++m) _Pragma("unroll") for (int k = 0; k < 2; ++k) dst[m][k] = *(const PG8_LAS bf16x8*)(lds + PG8_SA(b, h) + aoff + m * 2048 + k * 1024); } while (0)
; #define PG8_LDB(dst, b, h) do { _Pragma("unroll") for (int n = 0; n < 2; ++n) _Pragma("unroll") for (int k = 0; k < 2; ++k) dst[n][k] = *(const PG8_LAS bf16x8*)(lds + PG8_SB(b, h) + boff + n * 2048 + k * 1024); } while (0)
; #define PG8_WAIT_V(n) asm volatile("s_waitcnt vmcnt(" #n ")" ::: "memory")
; #define PG8_WAIT_L(n) asm volatile("s_waitcnt lgkmcnt(" #n ")" ::: "memory")
; #define PG8_BAR __builtin_amdgcn_s_barrier()
; #define PG8_SCHED __builtin_amdgcn_sched_barrier(0)
; template <class Epi, class Sched, bool ALIGN_EPI = false, bool SP2 = false>
; __device__ __forceinline__ void gemm_phase(PG8_LAS unsigned char* lds, const Gemm g, const Sched& S, const Epi& E, int wid) {
;     ...
;             const bool last = (t == nt - 2);
;             const char* a1 = cA + (size_t)(t + 1) * kstep;
;             const char* a2 = last ? nA : cA + (size_t)(t + 2) * kstep; const char* b2 = last ? nB : cB + (size_t)(t + 2) * kstep;
;             const char* a3 = a2 + kstep; const char* b3 = b2 + kstep;
;             if (last && has_next) S.a_ready(nxt);
;             if constexpr (SP2) {
;             PG8_LDB(B0, 0, 0); PG8_LDB(B1, 0, 1); PG8_SCHED; PG8_LDA(At, 0, 0); PG8_STAGE(PG8_SA(1, 1), a1 + hstepA, voffA);
;             PG8_WAIT_V(8); PG8_WAIT_L(0); PG8_BAR; PG8_MMA(0, 0, At, B0); PG8_MMA(0, 1, At, B1); PG8_BAR; PG8_SCHED;
;             PG8_LDA(At, 0, 1); PG8_STAGE_NT(PG8_SB(0, 0), b2, voffB); PG8_STAGE_NT(PG8_SB(0, 1), b2 + hstepB, voffB); PG8_STAGE(PG8_SA(0, 0), a2, voffA);
;             PG8_WAIT_V(8); PG8_WAIT_L(0); PG8_BAR; PG8_MMA(1, 0, At, B0); PG8_MMA(1, 1, At, B1); PG8_BAR; PG8_SCHED;
.LBB0_1037:
	ds_read_b128 v[104:107], v221
	ds_read_b128 v[116:119], v221 offset:1024
	ds_read_b128 v[128:131], v221 offset:2048
	ds_read_b128 v[140:143], v221 offset:3072
	ds_read_b128 v[144:147], v222
	ds_read_b128 v[148:151], v222 offset:1024
	ds_read_b128 v[152:155], v222 offset:2048
	ds_read_b128 v[156:159], v222 offset:3072
	s_add_u32 s52, s50, 0x100
	s_addc_u32 s53, s51, 0
	s_add_u32 s98, s50, 0x80
	s_addc_u32 s99, s51, 0
	s_add_u32 s100, s50, 0x104080
	s_addc_u32 s101, s51, 0
	s_cmp_eq_u32 s67, 60
	s_cselect_b32 s57, s7, s53
	s_cselect_b32 s56, s6, s52
	s_cselect_b32 s55, s49, s66
	s_cselect_b32 s54, s48, s65
	s_add_i32 m0, s17, 0xc000
	ds_read_b128 v[160:163], v223
	ds_read_b128 v[164:167], v223 offset:1024
	ds_read_b128 v[168:171], v223 offset:2048
	ds_read_b128 v[172:175], v223 offset:3072
	ds_read_b128 v[176:179], v223 offset:4096
	ds_read_b128 v[180:183], v223 offset:5120
	ds_read_b128 v[200:203], v223 offset:6144
	ds_read_b128 v[204:207], v223 offset:7168
	global_load_lds_dwordx4 v184, s[100:101]
	s_add_i32 m0, s17, 0xe000
	s_nop 0
	global_load_lds_dwordx4 v188, s[100:101]
	s_mov_b32 m0, s25
	s_nop 0
	global_load_lds_dwordx4 v184, s[98:99]
	s_mov_b32 m0, s29
	s_nop 0
	global_load_lds_dwordx4 v188, s[98:99]
	s_waitcnt vmcnt(8) lgkmcnt(0)
	s_barrier
	v_mfma_f32_16x16x32_bf16 v[136:139], v[104:107], v[160:163], v[136:139]
	v_mfma_f32_16x16x32_bf16 v[132:135], v[128:131], v[160:163], v[132:135]
	v_mfma_f32_16x16x32_bf16 v[112:115], v[104:107], v[168:171], v[112:115]
	v_mfma_f32_16x16x32_bf16 v[108:111], v[128:131], v[168:171], v[108:111]
	v_mfma_f32_16x16x32_bf16 v[92:95], v[104:107], v[176:179], v[92:95]
	v_mfma_f32_16x16x32_bf16 v[88:91], v[128:131], v[176:179], v[88:91]
	v_mfma_f32_16x16x32_bf16 v[76:79], v[104:107], v[200:203], v[76:79]
	v_mfma_f32_16x16x32_bf16 v[72:75], v[128:131], v[200:203], v[72:75]
	v_mfma_f32_16x16x32_bf16 v[136:139], v[116:119], v[164:167], v[136:139]
	v_mfma_f32_16x16x32_bf16 v[132:135], v[140:143], v[164:167], v[132:135]
	v_mfma_f32_16x16x32_bf16 v[112:115], v[116:119], v[172:175], v[112:115]
	v_mfma_f32_16x16x32_bf16 v[108:111], v[140:143], v[172:175], v[108:111]
	v_mfma_f32_16x16x32_bf16 v[92:95], v[116:119], v[180:183], v[92:95]
	v_mfma_f32_16x16x32_bf16 v[88:91], v[140:143], v[180:183], v[88:91]
	v_mfma_f32_16x16x32_bf16 v[76:79], v[116:119], v[204:207], v[76:79]
	v_mfma_f32_16x16x32_bf16 v[72:75], v[140:143], v[204:207], v[72:75]
	v_mfma_f32_16x16x32_bf16 v[124:127], v[144:147], v[160:163], v[124:127]
	v_mfma_f32_16x16x32_bf16 v[120:123], v[152:155], v[160:163], v[120:123]
	v_mfma_f32_16x16x32_bf16 v[100:103], v[144:147], v[168:171], v[100:103]
	v_mfma_f32_16x16x32_bf16 v[96:99], v[152:155], v[168:171], v[96:99]
	v_mfma_f32_16x16x32_bf16 v[84:87], v[144:147], v[176:179], v[84:87]
	v_mfma_f32_16x16x32_bf16 v[80:83], v[152:155], v[176:179], v[80:83]
	v_mfma_f32_16x16x32_bf16 v[68:71], v[144:147], v[200:203], v[68:71]
	v_mfma_f32_16x16x32_bf16 v[64:67], v[152:155], v[200:203], v[64:67]
	v_mfma_f32_16x16x32_bf16 v[124:127], v[148:151], v[164:167], v[124:127]
	v_mfma_f32_16x16x32_bf16 v[120:123], v[156:159], v[164:167], v[120:123]
	v_mfma_f32_16x16x32_bf16 v[100:103], v[148:151], v[172:175], v[100:103]
	v_mfma_f32_16x16x32_bf16 v[96:99], v[156:159], v[172:175], v[96:99]
	v_mfma_f32_16x16x32_bf16 v[84:87], v[148:151], v[180:183], v[84:87]
	v_mfma_f32_16x16x32_bf16 v[80:83], v[156:159], v[180:183], v[80:83]
	v_mfma_f32_16x16x32_bf16 v[68:71], v[148:151], v[204:207], v[68:71]
	v_mfma_f32_16x16x32_bf16 v[64:67], v[156:159], v[204:207], v[64:67]
	s_barrier
	s_add_i32 s50, s60, s9
	s_mov_b32 m0, s50
	ds_read_b128 v[160:163], v223 offset:16384
	ds_read_b128 v[164:167], v223 offset:17408
	ds_read_b128 v[168:171], v223 offset:18432
	ds_read_b128 v[172:175], v223 offset:19456
	ds_read_b128 v[176:179], v223 offset:20480
	ds_read_b128 v[180:183], v223 offset:21504
	ds_read_b128 v[200:203], v223 offset:22528
	ds_read_b128 v[204:207], v223 offset:23552
	global_load_lds_dwordx4 v186, s[54:55]
	s_add_i32 m0, s50, 0x2000
	s_add_u32 s50, s54, 0x104000
	s_addc_u32 s51, s55, 0
	s_add_i32 s68, s61, s9
	global_load_lds_dwordx4 v190, s[54:55]
	s_mov_b32 m0, s68
	s_nop 0
	global_load_lds_dwordx4 v186, s[50:51]
	s_add_i32 m0, s68, 0x2000
	s_nop 0
	global_load_lds_dwordx4 v190, s[50:51]
	s_waitcnt vmcnt(4) lgkmcnt(0)
	s_barrier
	v_mfma_f32_16x16x32_bf16 v[60:63], v[104:107], v[160:163], v[60:63]
	v_mfma_f32_16x16x32_bf16 v[56:59], v[128:131], v[160:163], v[56:59]
	v_mfma_f32_16x16x32_bf16 v[44:47], v[104:107], v[168:171], v[44:47]
	v_mfma_f32_16x16x32_bf16 v[40:43], v[128:131], v[168:171], v[40:43]
	v_mfma_f32_16x16x32_bf16 v[28:31], v[104:107], v[176:179], v[28:31]
	v_mfma_f32_16x16x32_bf16 v[24:27], v[128:131], v[176:179], v[24:27]
	v_mfma_f32_16x16x32_bf16 v[12:15], v[104:107], v[200:203], v[12:15]
	v_mfma_f32_16x16x32_bf16 v[8:11], v[128:131], v[200:203], v[8:11]
	v_mfma_f32_16x16x32_bf16 v[60:63], v[116:119], v[164:167], v[60:63]
	v_mfma_f32_16x16x32_bf16 v[56:59], v[140:143], v[164:167], v[56:59]
	v_mfma_f32_16x16x32_bf16 v[44:47], v[116:119], v[172:175], v[44:47]
	v_mfma_f32_16x16x32_bf16 v[40:43], v[140:143], v[172:175], v[40:43]
	v_mfma_f32_16x16x32_bf16 v[28:31], v[116:119], v[180:183], v[28:31]
	v_mfma_f32_16x16x32_bf16 v[24:27], v[140:143], v[180:183], v[24:27]
	v_mfma_f32_16x16x32_bf16 v[12:15], v[116:119], v[204:207], v[12:15]
	v_mfma_f32_16x16x32_bf16 v[8:11], v[140:143], v[204:207], v[8:11]
	v_mfma_f32_16x16x32_bf16 v[52:55], v[144:147], v[160:163], v[52:55]
	v_mfma_f32_16x16x32_bf16 v[48:51], v[152:155], v[160:163], v[48:51]
	v_mfma_f32_16x16x32_bf16 v[36:39], v[144:147], v[168:171], v[36:39]
	v_mfma_f32_16x16x32_bf16 v[32:35], v[152:155], v[168:171], v[32:35]
	v_mfma_f32_16x16x32_bf16 v[20:23], v[144:147], v[176:179], v[20:23]
	v_mfma_f32_16x16x32_bf16 v[16:19], v[152:155], v[176:179], v[16:19]
	v_mfma_f32_16x16x32_bf16 v[4:7], v[144:147], v[200:203], v[4:7]
	v_mfma_f32_16x16x32_bf16 v[0:3], v[152:155], v[200:203], v[0:3]
	v_mfma_f32_16x16x32_bf16 v[52:55], v[148:151], v[164:167], v[52:55]
	v_mfma_f32_16x16x32_bf16 v[48:51], v[156:159], v[164:167], v[48:51]
	v_mfma_f32_16x16x32_bf16 v[36:39], v[148:151], v[172:175], v[36:39]
	v_mfma_f32_16x16x32_bf16 v[32:35], v[156:159], v[172:175], v[32:35]
	v_mfma_f32_16x16x32_bf16 v[20:23], v[148:151], v[180:183], v[20:23]
	v_mfma_f32_16x16x32_bf16 v[16:19], v[156:159], v[180:183], v[16:19]
	v_mfma_f32_16x16x32_bf16 v[4:7], v[148:151], v[204:207], v[4:7]
	v_mfma_f32_16x16x32_bf16 v[0:3], v[156:159], v[204:207], v[0:3]
	s_barrier
; #define PG8_STAGE(bufoff, gbase, voff) do { _Pragma("unroll") for (int _i = 0; _i < 2; ++_i) \
;         __builtin_amdgcn_global_load_lds((const unsigned*)((const char*)(gbase) + (voff)[_i]), (PG8_LAS unsigned*)(lds + (bufoff) + ldsw + _i * 8192), 16, 0, 0); } while (0)
; #define PG8_STAGE_NT(bufoff, gbase, voff) do { _Pragma("unroll") for (int _i = 0; _i < 2; ++_i) \
;         __builtin_amdgcn_global_load_lds((const unsigned*)((const char*)(gbase) + (voff)[_i]), (PG8_LAS unsigned*)(lds + (bufoff) + ldsw + _i * 8192), 16, 0, PG8_B_AUX); } while (0)
; #define PG8_LDA(dst, b, h) do { _Pragma("unroll") for (int m = 0; m < 4; ++m) _Pragma("unroll") for (int k = 0; k < 2; ++k) dst[m][k] = *(const PG8_LAS bf16x8*)(lds + PG8_SA(b, h) + aoff + m * 2048 + k * 1024); } while (0)
; #define PG8_LDB(dst, b, h) do { _Pragma("unroll") for (int n = 0; n < 2; ++n) _Pragma("unroll") for (int k = 0; k < 2; ++k) dst[n][k] = *(const PG8_LAS bf16x8*)(lds + PG8_SB(b, h) + boff + n * 2048 + k * 1024); } while (0)
; #define PG8_MMA(ai, bj, At, Bt) do { __builtin_amdgcn_s_setprio(1); _Pragma("unroll") for (int m = 0; m < 4; ++m) _Pragma("unroll") for (int n = 0; n < 2; ++n) _Pragma("unroll") for (int k = 0; k < 2; ++k) \
;         acc[ai][bj][m][n] = __builtin_amdgcn_mfma_f32_16x16x32_bf16(Bt[n][k], At[m][k], acc[ai][bj][m][n], 0, 0, 0); __builtin_amdgcn_s_setprio(0); } while (0)
; #define PG8_WAIT_V(n) asm volatile("s_waitcnt vmcnt(" #n ")" ::: "memory")
; #define PG8_WAIT_L(n) asm volatile("s_waitcnt lgkmcnt(" #n ")" ::: "memory")
; #define PG8_BAR __builtin_amdgcn_s_barrier()
; #define PG8_SCHED __builtin_amdgcn_sched_barrier(0)
; template <class Epi, class Sched, bool ALIGN_EPI = false, bool SP2 = false>
; __device__ __forceinline__ void gemm_phase(PG8_LAS unsigned char* lds, const Gemm g, const Sched& S, const Epi& E, int wid) {
;     ...
;             PG8_LDB(B0, 1, 0); PG8_LDB(B1, 1, 1); PG8_SCHED; PG8_LDA(At, 1, 0); PG8_STAGE(PG8_SA(0, 1), a2 + hstepA, voffA);
;             PG8_WAIT_V(8); PG8_WAIT_L(0); PG8_BAR; PG8_MMA(0, 0, At, B0); PG8_MMA(0, 1, At, B1); PG8_BAR; PG8_SCHED;
;             PG8_LDA(At, 1, 1); PG8_STAGE_NT(PG8_SB(1, 0), b3, voffB); PG8_STAGE_NT(PG8_SB(1, 1), b3 + hstepB, voffB); PG8_STAGE(PG8_SA(1, 0), a3, voffA);
;             PG8_WAIT_V(8); PG8_WAIT_L(0); PG8_BAR; PG8_MMA(1, 0, At, B0); PG8_MMA(1, 1, At, B1); PG8_BAR; PG8_SCHED;
	s_add_i32 s68, 0, 0x18000
	v_add_u32_e32 v140, s68, v219
	s_add_i32 s69, 0, 0x1c000
	ds_read_b128 v[104:107], v140
	ds_read_b128 v[116:119], v140 offset:1024
	ds_read_b128 v[128:131], v140 offset:2048
	ds_read_b128 v[140:143], v140 offset:3072
	v_add_u32_e32 v156, s69, v219
	ds_read_b128 v[144:147], v156
	ds_read_b128 v[148:151], v156 offset:1024
	ds_read_b128 v[152:155], v156 offset:2048
	ds_read_b128 v[156:159], v156 offset:3072
	s_add_u32 s50, s56, 0x104000
	s_addc_u32 s51, s57, 0
	s_mov_b32 m0, s22
	ds_read_b128 v[160:163], v223 offset:32768
	ds_read_b128 v[164:167], v223 offset:33792
	ds_read_b128 v[168:171], v223 offset:34816
	ds_read_b128 v[172:175], v223 offset:35840
	ds_read_b128 v[176:179], v223 offset:36864
	ds_read_b128 v[180:183], v223 offset:37888
	ds_read_b128 v[200:203], v223 offset:38912
	ds_read_b128 v[204:207], v223 offset:39936
	global_load_lds_dwordx4 v184, s[50:51]
	s_mov_b32 m0, s23
	s_nop 0
	global_load_lds_dwordx4 v188, s[50:51]
	s_mov_b32 m0, s17
	s_nop 0
	global_load_lds_dwordx4 v184, s[56:57]
	s_mov_b32 m0, s19
	s_nop 0
	global_load_lds_dwordx4 v188, s[56:57]
	s_nop 0
	s_waitcnt vmcnt(8) lgkmcnt(0)
	s_barrier
	v_mfma_f32_16x16x32_bf16 v[136:139], v[104:107], v[160:163], v[136:139]
	v_mfma_f32_16x16x32_bf16 v[132:135], v[128:131], v[160:163], v[132:135]
	v_mfma_f32_16x16x32_bf16 v[112:115], v[104:107], v[168:171], v[112:115]
	v_mfma_f32_16x16x32_bf16 v[108:111], v[128:131], v[168:171], v[108:111]
	v_mfma_f32_16x16x32_bf16 v[92:95], v[104:107], v[176:179], v[92:95]
	v_mfma_f32_16x16x32_bf16 v[88:91], v[128:131], v[176:179], v[88:91]
	v_mfma_f32_16x16x32_bf16 v[76:79], v[104:107], v[200:203], v[76:79]
	v_mfma_f32_16x16x32_bf16 v[72:75], v[128:131], v[200:203], v[72:75]
	v_mfma_f32_16x16x32_bf16 v[136:139], v[116:119], v[164:167], v[136:139]
	v_mfma_f32_16x16x32_bf16 v[132:135], v[140:143], v[164:167], v[132:135]
	v_mfma_f32_16x16x32_bf16 v[112:115], v[116:119], v[172:175], v[112:115]
	v_mfma_f32_16x16x32_bf16 v[108:111], v[140:143], v[172:175], v[108:111]
	v_mfma_f32_16x16x32_bf16 v[92:95], v[116:119], v[180:183], v[92:95]
	v_mfma_f32_16x16x32_bf16 v[88:91], v[140:143], v[180:183], v[88:91]
	v_mfma_f32_16x16x32_bf16 v[76:79], v[116:119], v[204:207], v[76:79]
	v_mfma_f32_16x16x32_bf16 v[72:75], v[140:143], v[204:207], v[72:75]
	v_mfma_f32_16x16x32_bf16 v[124:127], v[144:147], v[160:163], v[124:127]
	v_mfma_f32_16x16x32_bf16 v[120:123], v[152:155], v[160:163], v[120:123]
	v_mfma_f32_16x16x32_bf16 v[100:103], v[144:147], v[168:171], v[100:103]
	v_mfma_f32_16x16x32_bf16 v[96:99], v[152:155], v[168:171], v[96:99]
	v_mfma_f32_16x16x32_bf16 v[84:87], v[144:147], v[176:179], v[84:87]
	v_mfma_f32_16x16x32_bf16 v[80:83], v[152:155], v[176:179], v[80:83]
	v_mfma_f32_16x16x32_bf16 v[68:71], v[144:147], v[200:203], v[68:71]
	v_mfma_f32_16x16x32_bf16 v[64:67], v[152:155], v[200:203], v[64:67]
	v_mfma_f32_16x16x32_bf16 v[124:127], v[148:151], v[164:167], v[124:127]
	v_mfma_f32_16x16x32_bf16 v[120:123], v[156:159], v[164:167], v[120:123]
	v_mfma_f32_16x16x32_bf16 v[100:103], v[148:151], v[172:175], v[100:103]
	v_mfma_f32_16x16x32_bf16 v[96:99], v[156:159], v[172:175], v[96:99]
	v_mfma_f32_16x16x32_bf16 v[84:87], v[148:151], v[180:183], v[84:87]
	v_mfma_f32_16x16x32_bf16 v[80:83], v[156:159], v[180:183], v[80:83]
	v_mfma_f32_16x16x32_bf16 v[68:71], v[148:151], v[204:207], v[68:71]
	v_mfma_f32_16x16x32_bf16 v[64:67], v[156:159], v[204:207], v[64:67]
	s_barrier
	s_add_i32 s50, s68, s9
	s_mov_b32 m0, s50
	s_add_u32 s98, s54, 0x80
	s_addc_u32 s99, s55, 0
	ds_read_b128 v[160:163], v223 offset:49152
	ds_read_b128 v[164:167], v223 offset:50176
	ds_read_b128 v[168:171], v223 offset:51200
	ds_read_b128 v[172:175], v223 offset:52224
	ds_read_b128 v[176:179], v223 offset:53248
	ds_read_b128 v[180:183], v223 offset:54272
	ds_read_b128 v[200:203], v223 offset:55296
	ds_read_b128 v[204:207], v223 offset:56320
	global_load_lds_dwordx4 v186, s[98:99]
	s_add_i32 m0, s50, 0x2000
	s_add_u32 s50, s54, 0x104080
	s_addc_u32 s51, s55, 0
	s_add_i32 s54, s69, s9
	global_load_lds_dwordx4 v190, s[98:99]
	s_mov_b32 m0, s54
	s_nop 0
	global_load_lds_dwordx4 v186, s[50:51]
	s_add_i32 m0, s54, 0x2000
	s_nop 0
	global_load_lds_dwordx4 v190, s[50:51]
	s_nop 0
	s_waitcnt vmcnt(4) lgkmcnt(0)
	s_barrier
	v_mfma_f32_16x16x32_bf16 v[60:63], v[104:107], v[160:163], v[60:63]
	v_mfma_f32_16x16x32_bf16 v[56:59], v[128:131], v[160:163], v[56:59]
	v_mfma_f32_16x16x32_bf16 v[44:47], v[104:107], v[168:171], v[44:47]
	v_mfma_f32_16x16x32_bf16 v[40:43], v[128:131], v[168:171], v[40:43]
	v_mfma_f32_16x16x32_bf16 v[28:31], v[104:107], v[176:179], v[28:31]
	v_mfma_f32_16x16x32_bf16 v[24:27], v[128:131], v[176:179], v[24:27]
	v_mfma_f32_16x16x32_bf16 v[12:15], v[104:107], v[200:203], v[12:15]
	v_mfma_f32_16x16x32_bf16 v[8:11], v[128:131], v[200:203], v[8:11]
	v_mfma_f32_16x16x32_bf16 v[60:63], v[116:119], v[164:167], v[60:63]
	v_mfma_f32_16x16x32_bf16 v[56:59], v[140:143], v[164:167], v[56:59]
	v_mfma_f32_16x16x32_bf16 v[44:47], v[116:119], v[172:175], v[44:47]
	v_mfma_f32_16x16x32_bf16 v[40:43], v[140:143], v[172:175], v[40:43]
	v_mfma_f32_16x16x32_bf16 v[28:31], v[116:119], v[180:183], v[28:31]
	v_mfma_f32_16x16x32_bf16 v[24:27], v[140:143], v[180:183], v[24:27]
	v_mfma_f32_16x16x32_bf16 v[12:15], v[116:119], v[204:207], v[12:15]
	v_mfma_f32_16x16x32_bf16 v[8:11], v[140:143], v[204:207], v[8:11]
	v_mfma_f32_16x16x32_bf16 v[52:55], v[144:147], v[160:163], v[52:55]
	v_mfma_f32_16x16x32_bf16 v[48:51], v[152:155], v[160:163], v[48:51]
	v_mfma_f32_16x16x32_bf16 v[36:39], v[144:147], v[168:171], v[36:39]
	v_mfma_f32_16x16x32_bf16 v[32:35], v[152:155], v[168:171], v[32:35]
	v_mfma_f32_16x16x32_bf16 v[20:23], v[144:147], v[176:179], v[20:23]
	v_mfma_f32_16x16x32_bf16 v[16:19], v[152:155], v[176:179], v[16:19]
	v_mfma_f32_16x16x32_bf16 v[4:7], v[144:147], v[200:203], v[4:7]
	v_mfma_f32_16x16x32_bf16 v[0:3], v[152:155], v[200:203], v[0:3]
	v_mfma_f32_16x16x32_bf16 v[52:55], v[148:151], v[164:167], v[52:55]
	v_mfma_f32_16x16x32_bf16 v[48:51], v[156:159], v[164:167], v[48:51]
	v_mfma_f32_16x16x32_bf16 v[36:39], v[148:151], v[172:175], v[36:39]
	v_mfma_f32_16x16x32_bf16 v[32:35], v[156:159], v[172:175], v[32:35]
	v_mfma_f32_16x16x32_bf16 v[20:23], v[148:151], v[180:183], v[20:23]
	v_mfma_f32_16x16x32_bf16 v[16:19], v[156:159], v[180:183], v[16:19]
	v_mfma_f32_16x16x32_bf16 v[4:7], v[148:151], v[204:207], v[4:7]
	v_mfma_f32_16x16x32_bf16 v[0:3], v[156:159], v[204:207], v[0:3]
	s_barrier
	s_add_i32 s67, s67, 2
	s_add_u32 s65, s65, 0x100
	s_addc_u32 s66, s66, 0
	s_cmp_gt_u32 s67, 61
	s_mov_b64 s[50:51], s[52:53]
	s_cbranch_scc0 .LBB0_1037
	s_and_b64 vcc, exec, s[46:47]
	s_cbranch_vccz .LBB0_1040
	s_barrier

; #define PG8_STAGE(bufoff, gbase, voff) do { _Pragma("unroll") for (int _i = 0; _i < 2; ++_i) \
;         __builtin_amdgcn_global_load_lds((const unsigned*)((const char*)(gbase) + (voff)[_i]), (PG8_LAS unsigned*)(lds + (bufoff) + ldsw + _i * 8192), 16, 0, 0); } while (0)
; #define PG8_STAGE_NT(bufoff, gbase, voff) do { _Pragma("unroll") for (int _i = 0; _i < 2; ++_i) \
;         __builtin_amdgcn_global_load_lds((const unsigned*)((const char*)(gbase) + (voff)[_i]), (PG8_LAS unsigned*)(lds + (bufoff) + ldsw + _i * 8192), 16, 0, PG8_B_AUX); } while (0)
; #define PG8_LDA(dst, b, h) do { _Pragma("unroll") for (int m = 0; m < 4; ++m) _Pragma("unroll") for (int k = 0; k < 2; ++k) dst[m][k] = *(const PG8_LAS bf16x8*)(lds + PG8_SA(b, h) + aoff + m * 2048 + k * 1024); } while (0)
; #define PG8_LDB(dst, b, h) do { _Pragma("unroll") for (int n = 0; n < 2; ++n) _Pragma("unroll") for (int k = 0; k < 2; ++k) dst[n][k] = *(const PG8_LAS bf16x8*)(lds + PG8_SB(b, h) + boff + n * 2048 + k * 1024); } while (0)
; #define PG8_WAIT_V(n) asm volatile("s_waitcnt vmcnt(" #n ")" ::: "memory")
; #define PG8_WAIT_L(n) asm volatile("s_waitcnt lgkmcnt(" #n ")" ::: "memory")
; #define PG8_BAR __builtin_amdgcn_s_barrier()
; #define PG8_SCHED __builtin_amdgcn_sched_barrier(0)
; template <class Epi, class Sched, bool ALIGN_EPI = false, bool SP2 = false>
; __device__ __forceinline__ void gemm_phase(PG8_LAS unsigned char* lds, const Gemm g, const Sched& S, const Epi& E, int wid) {
;     ...
;             const bool last = (t == nt - 2);
;             const char* a1 = cA + (size_t)(t + 1) * kstep;
;             const char* a2 = last ? nA : cA + (size_t)(t + 2) * kstep; const char* b2 = last ? nB : cB + (size_t)(t + 2) * kstep;
;             const char* a3 = a2 + kstep; const char* b3 = b2 + kstep;
;             if (last && has_next) S.a_ready(nxt);
;             if constexpr (SP2) {
;             PG8_LDB(B0, 0, 0); PG8_LDB(B1, 0, 1); PG8_SCHED; PG8_LDA(At, 0, 0); PG8_STAGE(PG8_SA(1, 1), a1 + hstepA, voffA);
;             PG8_WAIT_V(8); PG8_WAIT_L(0); PG8_BAR; PG8_MMA(0, 0, At, B0); PG8_MMA(0, 1, At, B1); PG8_BAR; PG8_SCHED;
;             PG8_LDA(At, 0, 1); PG8_STAGE_NT(PG8_SB(0, 0), b2, voffB); PG8_STAGE_NT(PG8_SB(0, 1), b2 + hstepB, voffB); PG8_STAGE(PG8_SA(0, 0), a2, voffA);
;             PG8_WAIT_V(8); PG8_WAIT_L(0); PG8_BAR; PG8_MMA(1, 0, At, B0); PG8_MMA(1, 1, At, B1); PG8_BAR; PG8_SCHED;
.LBB0_1133:
	ds_read_b128 v[144:147], v155
	ds_read_b128 v[148:151], v155 offset:1024
	ds_read_b128 v[160:163], v155 offset:2048
	ds_read_b128 v[164:167], v155 offset:3072
	ds_read_b128 v[168:171], v156
	ds_read_b128 v[172:175], v156 offset:1024
	ds_read_b128 v[176:179], v156 offset:2048
	ds_read_b128 v[180:183], v156 offset:3072
	s_add_u32 s4, s46, 0x100
	s_addc_u32 s5, s47, 0
	s_add_u32 s98, s46, 0x80
	s_addc_u32 s99, s47, 0
	s_add_u32 s100, s46, 0x104080
	s_addc_u32 s101, s47, 0
	s_cmp_eq_u32 s63, 60
	s_cselect_b32 s51, s43, s5
	s_cselect_b32 s50, s42, s4
	s_cselect_b32 s49, s45, s62
	s_cselect_b32 s48, s44, s61
	s_add_i32 m0, s22, 0xc000
	ds_read_b128 v[184:187], v157
	ds_read_b128 v[188:191], v157 offset:1024
	ds_read_b128 v[192:195], v157 offset:2048
	ds_read_b128 v[196:199], v157 offset:3072
	ds_read_b128 v[200:203], v157 offset:4096
	ds_read_b128 v[204:207], v157 offset:5120
	ds_read_b128 v[208:211], v157 offset:6144
	ds_read_b128 v[212:215], v157 offset:7168
	global_load_lds_dwordx4 v134, s[100:101]
	s_add_i32 m0, s22, 0xe000
	s_nop 0
	global_load_lds_dwordx4 v130, s[100:101]
	s_mov_b32 m0, s52
	s_nop 0
	global_load_lds_dwordx4 v134, s[98:99]
	s_mov_b32 m0, s53
	s_nop 0
	global_load_lds_dwordx4 v130, s[98:99]
	s_waitcnt vmcnt(8) lgkmcnt(0)
	s_barrier
	v_mfma_f32_16x16x32_bf16 v[112:115], v[144:147], v[184:187], v[112:115]
	v_mfma_f32_16x16x32_bf16 v[108:111], v[160:163], v[184:187], v[108:111]
	v_mfma_f32_16x16x32_bf16 v[104:107], v[144:147], v[192:195], v[104:107]
	v_mfma_f32_16x16x32_bf16 v[100:103], v[160:163], v[192:195], v[100:103]
	v_mfma_f32_16x16x32_bf16 v[92:95], v[144:147], v[200:203], v[92:95]
	v_mfma_f32_16x16x32_bf16 v[84:87], v[160:163], v[200:203], v[84:87]
	v_mfma_f32_16x16x32_bf16 v[76:79], v[144:147], v[208:211], v[76:79]
	v_mfma_f32_16x16x32_bf16 v[68:71], v[160:163], v[208:211], v[68:71]
	v_mfma_f32_16x16x32_bf16 v[112:115], v[148:151], v[188:191], v[112:115]
	v_mfma_f32_16x16x32_bf16 v[108:111], v[164:167], v[188:191], v[108:111]
	v_mfma_f32_16x16x32_bf16 v[104:107], v[148:151], v[196:199], v[104:107]
	v_mfma_f32_16x16x32_bf16 v[100:103], v[164:167], v[196:199], v[100:103]
	v_mfma_f32_16x16x32_bf16 v[92:95], v[148:151], v[204:207], v[92:95]
	v_mfma_f32_16x16x32_bf16 v[84:87], v[164:167], v[204:207], v[84:87]
	v_mfma_f32_16x16x32_bf16 v[76:79], v[148:151], v[212:215], v[76:79]
	v_mfma_f32_16x16x32_bf16 v[68:71], v[164:167], v[212:215], v[68:71]
	v_mfma_f32_16x16x32_bf16 v[124:127], v[168:171], v[184:187], v[124:127]
	v_mfma_f32_16x16x32_bf16 v[120:123], v[176:179], v[184:187], v[120:123]
	v_mfma_f32_16x16x32_bf16 v[116:119], v[168:171], v[192:195], v[116:119]
	v_mfma_f32_16x16x32_bf16 v[96:99], v[176:179], v[192:195], v[96:99]
	v_mfma_f32_16x16x32_bf16 v[88:91], v[168:171], v[200:203], v[88:91]
	v_mfma_f32_16x16x32_bf16 v[80:83], v[176:179], v[200:203], v[80:83]
	v_mfma_f32_16x16x32_bf16 v[72:75], v[168:171], v[208:211], v[72:75]
	v_mfma_f32_16x16x32_bf16 v[64:67], v[176:179], v[208:211], v[64:67]
	v_mfma_f32_16x16x32_bf16 v[124:127], v[172:175], v[188:191], v[124:127]
	v_mfma_f32_16x16x32_bf16 v[120:123], v[180:183], v[188:191], v[120:123]
	v_mfma_f32_16x16x32_bf16 v[116:119], v[172:175], v[196:199], v[116:119]
	v_mfma_f32_16x16x32_bf16 v[96:99], v[180:183], v[196:199], v[96:99]
	v_mfma_f32_16x16x32_bf16 v[88:91], v[172:175], v[204:207], v[88:91]
	v_mfma_f32_16x16x32_bf16 v[80:83], v[180:183], v[204:207], v[80:83]
	v_mfma_f32_16x16x32_bf16 v[72:75], v[172:175], v[212:215], v[72:75]
	v_mfma_f32_16x16x32_bf16 v[64:67], v[180:183], v[212:215], v[64:67]
	s_barrier
	s_add_i32 s46, s55, s9
	s_mov_b32 m0, s46
	ds_read_b128 v[184:187], v157 offset:16384
	ds_read_b128 v[188:191], v157 offset:17408
	ds_read_b128 v[192:195], v157 offset:18432
	ds_read_b128 v[196:199], v157 offset:19456
	ds_read_b128 v[200:203], v157 offset:20480
	ds_read_b128 v[204:207], v157 offset:21504
	ds_read_b128 v[208:211], v157 offset:22528
	ds_read_b128 v[212:215], v157 offset:23552
	global_load_lds_dwordx4 v132, s[48:49]
	s_add_i32 m0, s46, 0x2000
	s_add_u32 s46, s48, 0x104000
	s_addc_u32 s47, s49, 0
	s_add_i32 s64, s56, s9
	global_load_lds_dwordx4 v128, s[48:49]
	s_mov_b32 m0, s64
	s_nop 0
	global_load_lds_dwordx4 v132, s[46:47]
	s_add_i32 m0, s64, 0x2000
	s_nop 0
	global_load_lds_dwordx4 v128, s[46:47]
	s_waitcnt vmcnt(4) lgkmcnt(0)
	s_barrier
	v_mfma_f32_16x16x32_bf16 v[60:63], v[144:147], v[184:187], v[60:63]
	v_mfma_f32_16x16x32_bf16 v[52:55], v[160:163], v[184:187], v[52:55]
	v_mfma_f32_16x16x32_bf16 v[44:47], v[144:147], v[192:195], v[44:47]
	v_mfma_f32_16x16x32_bf16 v[36:39], v[160:163], v[192:195], v[36:39]
	v_mfma_f32_16x16x32_bf16 v[28:31], v[144:147], v[200:203], v[28:31]
	v_mfma_f32_16x16x32_bf16 v[20:23], v[160:163], v[200:203], v[20:23]
	v_mfma_f32_16x16x32_bf16 v[12:15], v[144:147], v[208:211], v[12:15]
	v_mfma_f32_16x16x32_bf16 v[4:7], v[160:163], v[208:211], v[4:7]
	v_mfma_f32_16x16x32_bf16 v[60:63], v[148:151], v[188:191], v[60:63]
	v_mfma_f32_16x16x32_bf16 v[52:55], v[164:167], v[188:191], v[52:55]
	v_mfma_f32_16x16x32_bf16 v[44:47], v[148:151], v[196:199], v[44:47]
	v_mfma_f32_16x16x32_bf16 v[36:39], v[164:167], v[196:199], v[36:39]
	v_mfma_f32_16x16x32_bf16 v[28:31], v[148:151], v[204:207], v[28:31]
	v_mfma_f32_16x16x32_bf16 v[20:23], v[164:167], v[204:207], v[20:23]
	v_mfma_f32_16x16x32_bf16 v[12:15], v[148:151], v[212:215], v[12:15]
	v_mfma_f32_16x16x32_bf16 v[4:7], v[164:167], v[212:215], v[4:7]
	v_mfma_f32_16x16x32_bf16 v[56:59], v[168:171], v[184:187], v[56:59]
	v_mfma_f32_16x16x32_bf16 v[48:51], v[176:179], v[184:187], v[48:51]
	v_mfma_f32_16x16x32_bf16 v[40:43], v[168:171], v[192:195], v[40:43]
	v_mfma_f32_16x16x32_bf16 v[32:35], v[176:179], v[192:195], v[32:35]
	v_mfma_f32_16x16x32_bf16 v[24:27], v[168:171], v[200:203], v[24:27]
	v_mfma_f32_16x16x32_bf16 v[16:19], v[176:179], v[200:203], v[16:19]
	v_mfma_f32_16x16x32_bf16 v[8:11], v[168:171], v[208:211], v[8:11]
	v_mfma_f32_16x16x32_bf16 v[0:3], v[176:179], v[208:211], v[0:3]
	v_mfma_f32_16x16x32_bf16 v[56:59], v[172:175], v[188:191], v[56:59]
	v_mfma_f32_16x16x32_bf16 v[48:51], v[180:183], v[188:191], v[48:51]
	v_mfma_f32_16x16x32_bf16 v[40:43], v[172:175], v[196:199], v[40:43]
	v_mfma_f32_16x16x32_bf16 v[32:35], v[180:183], v[196:199], v[32:35]
	v_mfma_f32_16x16x32_bf16 v[24:27], v[172:175], v[204:207], v[24:27]
	v_mfma_f32_16x16x32_bf16 v[16:19], v[180:183], v[204:207], v[16:19]
	v_mfma_f32_16x16x32_bf16 v[8:11], v[172:175], v[212:215], v[8:11]
	v_mfma_f32_16x16x32_bf16 v[0:3], v[180:183], v[212:215], v[0:3]
	s_barrier
; #define PG8_STAGE(bufoff, gbase, voff) do { _Pragma("unroll") for (int _i = 0; _i < 2; ++_i) \
;         __builtin_amdgcn_global_load_lds((const unsigned*)((const char*)(gbase) + (voff)[_i]), (PG8_LAS unsigned*)(lds + (bufoff) + ldsw + _i * 8192), 16, 0, 0); } while (0)
; #define PG8_STAGE_NT(bufoff, gbase, voff) do { _Pragma("unroll") for (int _i = 0; _i < 2; ++_i) \
;         __builtin_amdgcn_global_load_lds((const unsigned*)((const char*)(gbase) + (voff)[_i]), (PG8_LAS unsigned*)(lds + (bufoff) + ldsw + _i * 8192), 16, 0, PG8_B_AUX); } while (0)
; #define PG8_LDA(dst, b, h) do { _Pragma("unroll") for (int m = 0; m < 4; ++m) _Pragma("unroll") for (int k = 0; k < 2; ++k) dst[m][k] = *(const PG8_LAS bf16x8*)(lds + PG8_SA(b, h) + aoff + m * 2048 + k * 1024); } while (0)
; #define PG8_LDB(dst, b, h) do { _Pragma("unroll") for (int n = 0; n < 2; ++n) _Pragma("unroll") for (int k = 0; k < 2; ++k) dst[n][k] = *(const PG8_LAS bf16x8*)(lds + PG8_SB(b, h) + boff + n * 2048 + k * 1024); } while (0)
; #define PG8_MMA(ai, bj, At, Bt) do { __builtin_amdgcn_s_setprio(1); _Pragma("unroll") for (int m = 0; m < 4; ++m) _Pragma("unroll") for (int n = 0; n < 2; ++n) _Pragma("unroll") for (int k = 0; k < 2; ++k) \
;         acc[ai][bj][m][n] = __builtin_amdgcn_mfma_f32_16x16x32_bf16(Bt[n][k], At[m][k], acc[ai][bj][m][n], 0, 0, 0); __builtin_amdgcn_s_setprio(0); } while (0)
; #define PG8_WAIT_V(n) asm volatile("s_waitcnt vmcnt(" #n ")" ::: "memory")
; #define PG8_WAIT_L(n) asm volatile("s_waitcnt lgkmcnt(" #n ")" ::: "memory")
; #define PG8_BAR __builtin_amdgcn_s_barrier()
; #define PG8_SCHED __builtin_amdgcn_sched_barrier(0)
; template <class Epi, class Sched, bool ALIGN_EPI = false, bool SP2 = false>
; __device__ __forceinline__ void gemm_phase(PG8_LAS unsigned char* lds, const Gemm g, const Sched& S, const Epi& E, int wid) {
;     ...
;             PG8_LDB(B0, 1, 0); PG8_LDB(B1, 1, 1); PG8_SCHED; PG8_LDA(At, 1, 0); PG8_STAGE(PG8_SA(0, 1), a2 + hstepA, voffA);
;             PG8_WAIT_V(8); PG8_WAIT_L(0); PG8_BAR; PG8_MMA(0, 0, At, B0); PG8_MMA(0, 1, At, B1); PG8_BAR; PG8_SCHED;
;             PG8_LDA(At, 1, 1); PG8_STAGE_NT(PG8_SB(1, 0), b3, voffB); PG8_STAGE_NT(PG8_SB(1, 1), b3 + hstepB, voffB); PG8_STAGE(PG8_SA(1, 0), a3, voffA);
;             PG8_WAIT_V(8); PG8_WAIT_L(0); PG8_BAR; PG8_MMA(1, 0, At, B0); PG8_MMA(1, 1, At, B1); PG8_BAR; PG8_SCHED;
	s_add_i32 s64, 0, 0x18000
	v_add_u32_e32 v159, s64, v153
	s_add_i32 s65, 0, 0x1c000
	ds_read_b128 v[144:147], v159
	ds_read_b128 v[148:151], v159 offset:1024
	ds_read_b128 v[160:163], v159 offset:2048
	ds_read_b128 v[164:167], v159 offset:3072
	v_add_u32_e32 v159, s65, v153
	ds_read_b128 v[168:171], v159
	ds_read_b128 v[172:175], v159 offset:1024
	ds_read_b128 v[176:179], v159 offset:2048
	ds_read_b128 v[180:183], v159 offset:3072
	s_add_u32 s46, s50, 0x104000
	s_addc_u32 s47, s51, 0
	s_mov_b32 m0, s24
	ds_read_b128 v[184:187], v157 offset:32768
	ds_read_b128 v[188:191], v157 offset:33792
	ds_read_b128 v[192:195], v157 offset:34816
	ds_read_b128 v[196:199], v157 offset:35840
	ds_read_b128 v[200:203], v157 offset:36864
	ds_read_b128 v[204:207], v157 offset:37888
	ds_read_b128 v[208:211], v157 offset:38912
	ds_read_b128 v[212:215], v157 offset:39936
	global_load_lds_dwordx4 v134, s[46:47]
	s_mov_b32 m0, s25
	s_nop 0
	global_load_lds_dwordx4 v130, s[46:47]
	s_mov_b32 m0, s22
	s_nop 0
	global_load_lds_dwordx4 v134, s[50:51]
	s_mov_b32 m0, s23
	s_nop 0
	global_load_lds_dwordx4 v130, s[50:51]
	s_nop 0
	s_waitcnt vmcnt(8) lgkmcnt(0)
	s_barrier
	v_mfma_f32_16x16x32_bf16 v[112:115], v[144:147], v[184:187], v[112:115]
	v_mfma_f32_16x16x32_bf16 v[108:111], v[160:163], v[184:187], v[108:111]
	v_mfma_f32_16x16x32_bf16 v[104:107], v[144:147], v[192:195], v[104:107]
	v_mfma_f32_16x16x32_bf16 v[100:103], v[160:163], v[192:195], v[100:103]
	v_mfma_f32_16x16x32_bf16 v[92:95], v[144:147], v[200:203], v[92:95]
	v_mfma_f32_16x16x32_bf16 v[84:87], v[160:163], v[200:203], v[84:87]
	v_mfma_f32_16x16x32_bf16 v[76:79], v[144:147], v[208:211], v[76:79]
	v_mfma_f32_16x16x32_bf16 v[68:71], v[160:163], v[208:211], v[68:71]
	v_mfma_f32_16x16x32_bf16 v[112:115], v[148:151], v[188:191], v[112:115]
	v_mfma_f32_16x16x32_bf16 v[108:111], v[164:167], v[188:191], v[108:111]
	v_mfma_f32_16x16x32_bf16 v[104:107], v[148:151], v[196:199], v[104:107]
	v_mfma_f32_16x16x32_bf16 v[100:103], v[164:167], v[196:199], v[100:103]
	v_mfma_f32_16x16x32_bf16 v[92:95], v[148:151], v[204:207], v[92:95]
	v_mfma_f32_16x16x32_bf16 v[84:87], v[164:167], v[204:207], v[84:87]
	v_mfma_f32_16x16x32_bf16 v[76:79], v[148:151], v[212:215], v[76:79]
	v_mfma_f32_16x16x32_bf16 v[68:71], v[164:167], v[212:215], v[68:71]
	v_mfma_f32_16x16x32_bf16 v[124:127], v[168:171], v[184:187], v[124:127]
	v_mfma_f32_16x16x32_bf16 v[120:123], v[176:179], v[184:187], v[120:123]
	v_mfma_f32_16x16x32_bf16 v[116:119], v[168:171], v[192:195], v[116:119]
	v_mfma_f32_16x16x32_bf16 v[96:99], v[176:179], v[192:195], v[96:99]
	v_mfma_f32_16x16x32_bf16 v[88:91], v[168:171], v[200:203], v[88:91]
	v_mfma_f32_16x16x32_bf16 v[80:83], v[176:179], v[200:203], v[80:83]
	v_mfma_f32_16x16x32_bf16 v[72:75], v[168:171], v[208:211], v[72:75]
	v_mfma_f32_16x16x32_bf16 v[64:67], v[176:179], v[208:211], v[64:67]
	v_mfma_f32_16x16x32_bf16 v[124:127], v[172:175], v[188:191], v[124:127]
	v_mfma_f32_16x16x32_bf16 v[120:123], v[180:183], v[188:191], v[120:123]
	v_mfma_f32_16x16x32_bf16 v[116:119], v[172:175], v[196:199], v[116:119]
	v_mfma_f32_16x16x32_bf16 v[96:99], v[180:183], v[196:199], v[96:99]
	v_mfma_f32_16x16x32_bf16 v[88:91], v[172:175], v[204:207], v[88:91]
	v_mfma_f32_16x16x32_bf16 v[80:83], v[180:183], v[204:207], v[80:83]
	v_mfma_f32_16x16x32_bf16 v[72:75], v[172:175], v[212:215], v[72:75]
	v_mfma_f32_16x16x32_bf16 v[64:67], v[180:183], v[212:215], v[64:67]
	s_barrier
	s_add_i32 s46, s64, s9
	s_mov_b32 m0, s46
	s_add_u32 s98, s48, 0x80
	s_addc_u32 s99, s49, 0
	ds_read_b128 v[184:187], v157 offset:49152
	ds_read_b128 v[188:191], v157 offset:50176
	ds_read_b128 v[192:195], v157 offset:51200
	ds_read_b128 v[196:199], v157 offset:52224
	ds_read_b128 v[200:203], v157 offset:53248
	ds_read_b128 v[204:207], v157 offset:54272
	ds_read_b128 v[208:211], v157 offset:55296
	ds_read_b128 v[212:215], v157 offset:56320
	global_load_lds_dwordx4 v132, s[98:99]
	s_add_i32 m0, s46, 0x2000
	s_add_u32 s46, s48, 0x104080
	s_addc_u32 s47, s49, 0
	s_add_i32 s48, s65, s9
	global_load_lds_dwordx4 v128, s[98:99]
	s_mov_b32 m0, s48
	s_nop 0
	global_load_lds_dwordx4 v132, s[46:47]
	s_add_i32 m0, s48, 0x2000
	s_nop 0
	global_load_lds_dwordx4 v128, s[46:47]
	s_nop 0
	s_waitcnt vmcnt(4) lgkmcnt(0)
	s_barrier
	v_mfma_f32_16x16x32_bf16 v[60:63], v[144:147], v[184:187], v[60:63]
	v_mfma_f32_16x16x32_bf16 v[52:55], v[160:163], v[184:187], v[52:55]
	v_mfma_f32_16x16x32_bf16 v[44:47], v[144:147], v[192:195], v[44:47]
	v_mfma_f32_16x16x32_bf16 v[36:39], v[160:163], v[192:195], v[36:39]
	v_mfma_f32_16x16x32_bf16 v[28:31], v[144:147], v[200:203], v[28:31]
	v_mfma_f32_16x16x32_bf16 v[20:23], v[160:163], v[200:203], v[20:23]
	v_mfma_f32_16x16x32_bf16 v[12:15], v[144:147], v[208:211], v[12:15]
	v_mfma_f32_16x16x32_bf16 v[4:7], v[160:163], v[208:211], v[4:7]
	v_mfma_f32_16x16x32_bf16 v[60:63], v[148:151], v[188:191], v[60:63]
	v_mfma_f32_16x16x32_bf16 v[52:55], v[164:167], v[188:191], v[52:55]
	v_mfma_f32_16x16x32_bf16 v[44:47], v[148:151], v[196:199], v[44:47]
	v_mfma_f32_16x16x32_bf16 v[36:39], v[164:167], v[196:199], v[36:39]
	v_mfma_f32_16x16x32_bf16 v[28:31], v[148:151], v[204:207], v[28:31]
	v_mfma_f32_16x16x32_bf16 v[20:23], v[164:167], v[204:207], v[20:23]
	v_mfma_f32_16x16x32_bf16 v[12:15], v[148:151], v[212:215], v[12:15]
	v_mfma_f32_16x16x32_bf16 v[4:7], v[164:167], v[212:215], v[4:7]
	v_mfma_f32_16x16x32_bf16 v[56:59], v[168:171], v[184:187], v[56:59]
	v_mfma_f32_16x16x32_bf16 v[48:51], v[176:179], v[184:187], v[48:51]
	v_mfma_f32_16x16x32_bf16 v[40:43], v[168:171], v[192:195], v[40:43]
	v_mfma_f32_16x16x32_bf16 v[32:35], v[176:179], v[192:195], v[32:35]
	v_mfma_f32_16x16x32_bf16 v[24:27], v[168:171], v[200:203], v[24:27]
	v_mfma_f32_16x16x32_bf16 v[16:19], v[176:179], v[200:203], v[16:19]
	v_mfma_f32_16x16x32_bf16 v[8:11], v[168:171], v[208:211], v[8:11]
	v_mfma_f32_16x16x32_bf16 v[0:3], v[176:179], v[208:211], v[0:3]
	v_mfma_f32_16x16x32_bf16 v[56:59], v[172:175], v[188:191], v[56:59]
	v_mfma_f32_16x16x32_bf16 v[48:51], v[180:183], v[188:191], v[48:51]
	v_mfma_f32_16x16x32_bf16 v[40:43], v[172:175], v[196:199], v[40:43]
	v_mfma_f32_16x16x32_bf16 v[32:35], v[180:183], v[196:199], v[32:35]
	v_mfma_f32_16x16x32_bf16 v[24:27], v[172:175], v[204:207], v[24:27]
	v_mfma_f32_16x16x32_bf16 v[16:19], v[180:183], v[204:207], v[16:19]
	v_mfma_f32_16x16x32_bf16 v[8:11], v[172:175], v[212:215], v[8:11]
	v_mfma_f32_16x16x32_bf16 v[0:3], v[180:183], v[212:215], v[0:3]
	s_barrier
	s_add_i32 s63, s63, 2
	s_add_u32 s61, s61, 0x100
	s_addc_u32 s62, s62, 0
	s_cmp_gt_u32 s63, 61
	s_mov_b64 s[46:47], s[4:5]
	s_cbranch_scc0 .LBB0_1133
	s_and_b64 vcc, exec, s[40:41]
	s_cbranch_vccz .LBB0_1136
	s_barrier
